# GEMM K-loop MFMA loop-nest order Nnbm, k innermost
# baseline (speedup 1.0000x reference)
; #define PG8_STAGE(bufoff, gbase, voff) do { _Pragma("unroll") for (int _i = 0; _i < 2; ++_i) \
;         __builtin_amdgcn_global_load_lds((const unsigned*)((const char*)(gbase) + (voff)[_i]), (PG8_LAS unsigned*)(lds + (bufoff) + ldsw + _i * 8192), 16, 0, 0); } while (0)
; #define PG8_LDA(dst, b, h) do { _Pragma("unroll") for (int m = 0; m < 4; ++m) _Pragma("unroll") for (int k = 0; k < 2; ++k) dst[m][k] = *(const PG8_LAS bf16x8*)(lds + PG8_SA(b, h) + aoff + m * 2048 + k * 1024); } while (0)
; #define PG8_LDB(dst, b, h) do { _Pragma("unroll") for (int n = 0; n < 2; ++n) _Pragma("unroll") for (int k = 0; k < 2; ++k) dst[n][k] = *(const PG8_LAS bf16x8*)(lds + PG8_SB(b, h) + boff + n * 2048 + k * 1024); } while (0)
; #define PG8_MMA(ai, bj, At, Bt) do { __builtin_amdgcn_s_setprio(1); _Pragma("unroll") for (int m = 0; m < 4; ++m) _Pragma("unroll") for (int n = 0; n < 2; ++n) _Pragma("unroll") for (int k = 0; k < 2; ++k) \
;         acc[ai][bj][m][n] = __builtin_amdgcn_mfma_f32_16x16x32_bf16(Bt[n][k], At[m][k], acc[ai][bj][m][n], 0, 0, 0); __builtin_amdgcn_s_setprio(0); } while (0)
; #define PG8_WAIT_V(n) asm volatile("s_waitcnt vmcnt(" #n ")" ::: "memory")
; #define PG8_BAR __builtin_amdgcn_s_barrier()
; template <class Epi, class Sched, bool ALIGN_EPI = false, bool SP2 = false>
; __device__ __forceinline__ void gemm_phase(PG8_LAS unsigned char* lds, const Gemm g, const Sched& S, const Epi& E) {
;     ...
;         for (int t = 0; t < nt; t += 2) {
;             const bool last = (t == nt - 2);
;             const char* a1 = cA + (size_t)(t + 1) * kstep;
;             const char* a2 = last ? nA : cA + (size_t)(t + 2) * kstep; const char* b2 = last ? nB : cB + (size_t)(t + 2) * kstep;
;             const char* a3 = a2 + kstep; const char* b3 = b2 + kstep;
;             if (last && has_next) S.a_ready(nxt);
;             if constexpr (SP2) {
;             PG8_LDB(B0, 0, 0); PG8_LDB(B1, 0, 1); PG8_SCHED; PG8_LDA(At, 0, 0); PG8_STAGE(PG8_SA(1, 1), a1 + hstep, voffA);
;             PG8_WAIT_V(8); PG8_WAIT_L(0); PG8_BAR; PG8_MMA(0, 0, At, B0); PG8_MMA(0, 1, At, B1); PG8_BAR; PG8_SCHED;
;             PG8_LDA(At, 0, 1); PG8_STAGE(PG8_SB(0, 0), b2, voffB); PG8_STAGE(PG8_SB(0, 1), b2 + hstep, voffB); PG8_STAGE(PG8_SA(0, 0), a2, voffA);
;             PG8_WAIT_V(8); PG8_WAIT_L(0); PG8_BAR; PG8_MMA(1, 0, At, B0); PG8_MMA(1, 1, At, B1); PG8_BAR; PG8_SCHED;
.LBB0_132:
	s_add_u32 s18, s46, 0xfffc0080
	s_addc_u32 s38, s47, -1
	s_add_i32 s39, 0, 0x10000
	s_cmp_eq_u32 s85, 12
	s_cselect_b32 s81, s33, s38
	s_cselect_b32 s80, s73, s18
	v_add_u32_e32 v0, s39, v176
	s_cselect_b32 s45, s75, s84
	s_cselect_b32 s44, s82, s83
	s_add_i32 s18, 0, 0x14000
	ds_read_b128 v[144:147], v0
	ds_read_b128 v[148:151], v0 offset:1024
	ds_read_b128 v[152:155], v0 offset:2048
	ds_read_b128 v[156:159], v0 offset:3072
	v_add_u32_e32 v0, s18, v176
	ds_read_b128 v[160:163], v0
	ds_read_b128 v[164:167], v0 offset:1024
	ds_read_b128 v[168:171], v0 offset:2048
	ds_read_b128 v[172:175], v0 offset:3072
	v_lshl_add_u64 v[218:219], s[46:47], 0, v[140:141]
	s_add_i32 m0, s92, 0xc000
	ds_read_b128 v[180:183], v178
	ds_read_b128 v[184:187], v178 offset:1024
	ds_read_b128 v[188:191], v178 offset:2048
	ds_read_b128 v[192:195], v178 offset:3072
	ds_read_b128 v[202:205], v178 offset:4096
	ds_read_b128 v[206:209], v178 offset:5120
	ds_read_b128 v[210:213], v178 offset:6144
	ds_read_b128 v[214:217], v178 offset:7168
	global_load_lds_dwordx4 v[218:219], off
	v_lshl_add_u64 v[218:219], s[46:47], 0, v[142:143]
	s_add_i32 m0, s92, 0xe000
	s_nop 0
	global_load_lds_dwordx4 v[218:219], off
	s_waitcnt vmcnt(8)
	s_waitcnt lgkmcnt(0)
	s_barrier
	s_setprio 1
	s_waitcnt lgkmcnt(0)
	v_mfma_f32_16x16x32_bf16 v[118:121], v[144:147], v[180:183], v[118:121]
	v_mfma_f32_16x16x32_bf16 v[118:121], v[148:151], v[184:187], v[118:121]
	v_mfma_f32_16x16x32_bf16 v[102:105], v[144:147], v[188:191], v[102:105]
	v_mfma_f32_16x16x32_bf16 v[102:105], v[148:151], v[192:195], v[102:105]
	v_mfma_f32_16x16x32_bf16 v[86:89], v[144:147], v[202:205], v[86:89]
	v_mfma_f32_16x16x32_bf16 v[86:89], v[148:151], v[206:209], v[86:89]
	v_mfma_f32_16x16x32_bf16 v[70:73], v[144:147], v[210:213], v[70:73]
	v_mfma_f32_16x16x32_bf16 v[70:73], v[148:151], v[214:217], v[70:73]
	v_mfma_f32_16x16x32_bf16 v[126:129], v[160:163], v[180:183], v[126:129]
	v_mfma_f32_16x16x32_bf16 v[126:129], v[164:167], v[184:187], v[126:129]
	v_mfma_f32_16x16x32_bf16 v[110:113], v[160:163], v[188:191], v[110:113]
	v_mfma_f32_16x16x32_bf16 v[110:113], v[164:167], v[192:195], v[110:113]
	v_mfma_f32_16x16x32_bf16 v[94:97], v[160:163], v[202:205], v[94:97]
	v_mfma_f32_16x16x32_bf16 v[94:97], v[164:167], v[206:209], v[94:97]
	v_mfma_f32_16x16x32_bf16 v[78:81], v[160:163], v[210:213], v[78:81]
	v_mfma_f32_16x16x32_bf16 v[78:81], v[164:167], v[214:217], v[78:81]
	v_mfma_f32_16x16x32_bf16 v[114:117], v[152:155], v[180:183], v[114:117]
	v_mfma_f32_16x16x32_bf16 v[114:117], v[156:159], v[184:187], v[114:117]
	v_mfma_f32_16x16x32_bf16 v[98:101], v[152:155], v[188:191], v[98:101]
	v_mfma_f32_16x16x32_bf16 v[98:101], v[156:159], v[192:195], v[98:101]
	v_mfma_f32_16x16x32_bf16 v[82:85], v[152:155], v[202:205], v[82:85]
	v_mfma_f32_16x16x32_bf16 v[82:85], v[156:159], v[206:209], v[82:85]
	v_mfma_f32_16x16x32_bf16 v[66:69], v[152:155], v[210:213], v[66:69]
	v_mfma_f32_16x16x32_bf16 v[66:69], v[156:159], v[214:217], v[66:69]
	v_mfma_f32_16x16x32_bf16 v[122:125], v[168:171], v[180:183], v[122:125]
	v_mfma_f32_16x16x32_bf16 v[122:125], v[172:175], v[184:187], v[122:125]
	v_mfma_f32_16x16x32_bf16 v[106:109], v[168:171], v[188:191], v[106:109]
	v_mfma_f32_16x16x32_bf16 v[106:109], v[172:175], v[192:195], v[106:109]
	v_mfma_f32_16x16x32_bf16 v[90:93], v[168:171], v[202:205], v[90:93]
	v_mfma_f32_16x16x32_bf16 v[90:93], v[172:175], v[206:209], v[90:93]
	v_mfma_f32_16x16x32_bf16 v[74:77], v[168:171], v[210:213], v[74:77]
	v_mfma_f32_16x16x32_bf16 v[74:77], v[172:175], v[214:217], v[74:77]
	s_setprio 0
	s_barrier
	s_add_i32 s38, s39, s91
	v_lshl_add_u64 v[218:219], s[44:45], 0, v[134:135]
	s_mov_b32 m0, s38
	ds_read_b128 v[180:183], v178 offset:16384
	ds_read_b128 v[184:187], v178 offset:17408
	ds_read_b128 v[188:191], v178 offset:18432
	ds_read_b128 v[192:195], v178 offset:19456
	ds_read_b128 v[202:205], v178 offset:20480
	ds_read_b128 v[206:209], v178 offset:21504
	ds_read_b128 v[210:213], v178 offset:22528
	ds_read_b128 v[214:217], v178 offset:23552
	global_load_lds_dwordx4 v[218:219], off
	s_add_i32 m0, s38, 0x2000
	s_add_u32 s38, s44, 0x40000
	v_lshl_add_u64 v[220:221], s[44:45], 0, v[130:131]
	s_addc_u32 s39, s45, 0
	s_add_i32 s18, s18, s91
	global_load_lds_dwordx4 v[220:221], off
	v_lshl_add_u64 v[222:223], s[38:39], 0, v[134:135]
	s_mov_b32 m0, s18
	v_lshl_add_u64 v[224:225], s[80:81], 0, v[132:133]
	global_load_lds_dwordx4 v[222:223], off
	v_lshl_add_u64 v[222:223], s[38:39], 0, v[130:131]
	s_add_i32 m0, s18, 0x2000
	s_nop 0
	global_load_lds_dwordx4 v[222:223], off
	v_lshl_add_u64 v[222:223], s[80:81], 0, v[136:137]
	s_mov_b32 m0, s92
	s_nop 0
	global_load_lds_dwordx4 v[222:223], off
	s_mov_b32 m0, s93
	s_nop 0
	global_load_lds_dwordx4 v[224:225], off
	s_waitcnt vmcnt(8)
	s_waitcnt lgkmcnt(0)
	s_barrier
; #define PG8_STAGE(bufoff, gbase, voff) do { _Pragma("unroll") for (int _i = 0; _i < 2; ++_i) \
;         __builtin_amdgcn_global_load_lds((const unsigned*)((const char*)(gbase) + (voff)[_i]), (PG8_LAS unsigned*)(lds + (bufoff) + ldsw + _i * 8192), 16, 0, 0); } while (0)
; #define PG8_LDA(dst, b, h) do { _Pragma("unroll") for (int m = 0; m < 4; ++m) _Pragma("unroll") for (int k = 0; k < 2; ++k) dst[m][k] = *(const PG8_LAS bf16x8*)(lds + PG8_SA(b, h) + aoff + m * 2048 + k * 1024); } while (0)
; #define PG8_LDB(dst, b, h) do { _Pragma("unroll") for (int n = 0; n < 2; ++n) _Pragma("unroll") for (int k = 0; k < 2; ++k) dst[n][k] = *(const PG8_LAS bf16x8*)(lds + PG8_SB(b, h) + boff + n * 2048 + k * 1024); } while (0)
; #define PG8_MMA(ai, bj, At, Bt) do { __builtin_amdgcn_s_setprio(1); _Pragma("unroll") for (int m = 0; m < 4; ++m) _Pragma("unroll") for (int n = 0; n < 2; ++n) _Pragma("unroll") for (int k = 0; k < 2; ++k) \
;         acc[ai][bj][m][n] = __builtin_amdgcn_mfma_f32_16x16x32_bf16(Bt[n][k], At[m][k], acc[ai][bj][m][n], 0, 0, 0); __builtin_amdgcn_s_setprio(0); } while (0)
; #define PG8_WAIT_V(n) asm volatile("s_waitcnt vmcnt(" #n ")" ::: "memory")
; #define PG8_WAIT_L(n) asm volatile("s_waitcnt lgkmcnt(" #n ")" ::: "memory")
; #define PG8_BAR __builtin_amdgcn_s_barrier()
; #define PG8_SCHED __builtin_amdgcn_sched_barrier(0)
; template <class Epi, class Sched, bool ALIGN_EPI = false, bool SP2 = false>
; __device__ __forceinline__ void gemm_phase(PG8_LAS unsigned char* lds, const Gemm g, const Sched& S, const Epi& E) {
;     ...
;             PG8_WAIT_V(8); PG8_WAIT_L(0); PG8_BAR; PG8_MMA(1, 0, At, B0); PG8_MMA(1, 1, At, B1); PG8_BAR; PG8_SCHED;
;             PG8_LDB(B0, 1, 0); PG8_LDB(B1, 1, 1); PG8_SCHED; PG8_LDA(At, 1, 0); PG8_STAGE(PG8_SA(0, 1), a2 + hstep, voffA);
;             PG8_WAIT_V(8); PG8_WAIT_L(0); PG8_BAR; PG8_MMA(0, 0, At, B0); PG8_MMA(0, 1, At, B1); PG8_BAR; PG8_SCHED;
	s_setprio 1
	s_waitcnt lgkmcnt(0)
	v_mfma_f32_16x16x32_bf16 v[54:57], v[144:147], v[180:183], v[54:57]
	v_mfma_f32_16x16x32_bf16 v[54:57], v[148:151], v[184:187], v[54:57]
	v_mfma_f32_16x16x32_bf16 v[38:41], v[144:147], v[188:191], v[38:41]
	v_mfma_f32_16x16x32_bf16 v[38:41], v[148:151], v[192:195], v[38:41]
	v_mfma_f32_16x16x32_bf16 v[22:25], v[144:147], v[202:205], v[22:25]
	v_mfma_f32_16x16x32_bf16 v[22:25], v[148:151], v[206:209], v[22:25]
	v_mfma_f32_16x16x32_bf16 v[6:9], v[144:147], v[210:213], v[6:9]
	v_mfma_f32_16x16x32_bf16 v[6:9], v[148:151], v[214:217], v[6:9]
	v_mfma_f32_16x16x32_bf16 v[62:65], v[160:163], v[180:183], v[62:65]
	v_mfma_f32_16x16x32_bf16 v[62:65], v[164:167], v[184:187], v[62:65]
	v_mfma_f32_16x16x32_bf16 v[46:49], v[160:163], v[188:191], v[46:49]
	v_mfma_f32_16x16x32_bf16 v[46:49], v[164:167], v[192:195], v[46:49]
	v_mfma_f32_16x16x32_bf16 v[30:33], v[160:163], v[202:205], v[30:33]
	v_mfma_f32_16x16x32_bf16 v[30:33], v[164:167], v[206:209], v[30:33]
	v_mfma_f32_16x16x32_bf16 v[10:13], v[160:163], v[210:213], v[10:13]
	v_mfma_f32_16x16x32_bf16 v[10:13], v[164:167], v[214:217], v[10:13]
	v_mfma_f32_16x16x32_bf16 v[50:53], v[152:155], v[180:183], v[50:53]
	v_mfma_f32_16x16x32_bf16 v[50:53], v[156:159], v[184:187], v[50:53]
	v_mfma_f32_16x16x32_bf16 v[34:37], v[152:155], v[188:191], v[34:37]
	v_mfma_f32_16x16x32_bf16 v[34:37], v[156:159], v[192:195], v[34:37]
	v_mfma_f32_16x16x32_bf16 v[18:21], v[152:155], v[202:205], v[18:21]
	v_mfma_f32_16x16x32_bf16 v[18:21], v[156:159], v[206:209], v[18:21]
	v_mfma_f32_16x16x32_bf16 v[2:5], v[152:155], v[210:213], v[2:5]
	v_mfma_f32_16x16x32_bf16 v[2:5], v[156:159], v[214:217], v[2:5]
	v_mfma_f32_16x16x32_bf16 v[58:61], v[168:171], v[180:183], v[58:61]
	v_mfma_f32_16x16x32_bf16 v[58:61], v[172:175], v[184:187], v[58:61]
	v_mfma_f32_16x16x32_bf16 v[42:45], v[168:171], v[188:191], v[42:45]
	v_mfma_f32_16x16x32_bf16 v[42:45], v[172:175], v[192:195], v[42:45]
	v_mfma_f32_16x16x32_bf16 v[26:29], v[168:171], v[202:205], v[26:29]
	v_mfma_f32_16x16x32_bf16 v[26:29], v[172:175], v[206:209], v[26:29]
	v_mfma_f32_16x16x32_bf16 v[14:17], v[168:171], v[210:213], v[14:17]
	v_mfma_f32_16x16x32_bf16 v[14:17], v[172:175], v[214:217], v[14:17]
	s_setprio 0
	s_barrier
	s_add_i32 s18, 0, 0x18000
	v_add_u32_e32 v0, s18, v176
	s_add_i32 vcc_lo, 0, 0x1c000
	ds_read_b128 v[144:147], v0
	ds_read_b128 v[148:151], v0 offset:1024
	ds_read_b128 v[152:155], v0 offset:2048
	ds_read_b128 v[156:159], v0 offset:3072
	v_add_u32_e32 v0, vcc_lo, v176
	ds_read_b128 v[160:163], v0
	ds_read_b128 v[164:167], v0 offset:1024
	ds_read_b128 v[168:171], v0 offset:2048
	ds_read_b128 v[172:175], v0 offset:3072
	s_add_u32 s38, s80, 0x40000
	s_addc_u32 s39, s81, 0
	s_mov_b32 m0, s94
	v_lshl_add_u64 v[226:227], s[38:39], 0, v[136:137]
	ds_read_b128 v[180:183], v178 offset:32768
	ds_read_b128 v[184:187], v178 offset:33792
	ds_read_b128 v[188:191], v178 offset:34816
	ds_read_b128 v[192:195], v178 offset:35840
	ds_read_b128 v[202:205], v178 offset:36864
	ds_read_b128 v[206:209], v178 offset:37888
	ds_read_b128 v[210:213], v178 offset:38912
	ds_read_b128 v[214:217], v178 offset:39936
	global_load_lds_dwordx4 v[226:227], off
	v_lshl_add_u64 v[226:227], s[38:39], 0, v[132:133]
	s_mov_b32 m0, s95
	s_nop 0
	global_load_lds_dwordx4 v[226:227], off
	s_waitcnt vmcnt(8)
	s_waitcnt lgkmcnt(0)
	s_barrier
	s_setprio 1
	s_waitcnt lgkmcnt(0)
	v_mfma_f32_16x16x32_bf16 v[118:121], v[144:147], v[180:183], v[118:121]
	v_mfma_f32_16x16x32_bf16 v[118:121], v[148:151], v[184:187], v[118:121]
	v_mfma_f32_16x16x32_bf16 v[102:105], v[144:147], v[188:191], v[102:105]
	v_mfma_f32_16x16x32_bf16 v[102:105], v[148:151], v[192:195], v[102:105]
	v_mfma_f32_16x16x32_bf16 v[86:89], v[144:147], v[202:205], v[86:89]
	v_mfma_f32_16x16x32_bf16 v[86:89], v[148:151], v[206:209], v[86:89]
	v_mfma_f32_16x16x32_bf16 v[70:73], v[144:147], v[210:213], v[70:73]
	v_mfma_f32_16x16x32_bf16 v[70:73], v[148:151], v[214:217], v[70:73]
	v_mfma_f32_16x16x32_bf16 v[126:129], v[160:163], v[180:183], v[126:129]
	v_mfma_f32_16x16x32_bf16 v[126:129], v[164:167], v[184:187], v[126:129]
	v_mfma_f32_16x16x32_bf16 v[110:113], v[160:163], v[188:191], v[110:113]
	v_mfma_f32_16x16x32_bf16 v[110:113], v[164:167], v[192:195], v[110:113]
	v_mfma_f32_16x16x32_bf16 v[94:97], v[160:163], v[202:205], v[94:97]
	v_mfma_f32_16x16x32_bf16 v[94:97], v[164:167], v[206:209], v[94:97]
	v_mfma_f32_16x16x32_bf16 v[78:81], v[160:163], v[210:213], v[78:81]
	v_mfma_f32_16x16x32_bf16 v[78:81], v[164:167], v[214:217], v[78:81]
	v_mfma_f32_16x16x32_bf16 v[114:117], v[152:155], v[180:183], v[114:117]
	v_mfma_f32_16x16x32_bf16 v[114:117], v[156:159], v[184:187], v[114:117]
	v_mfma_f32_16x16x32_bf16 v[98:101], v[152:155], v[188:191], v[98:101]
	v_mfma_f32_16x16x32_bf16 v[98:101], v[156:159], v[192:195], v[98:101]
	v_mfma_f32_16x16x32_bf16 v[82:85], v[152:155], v[202:205], v[82:85]
	v_mfma_f32_16x16x32_bf16 v[82:85], v[156:159], v[206:209], v[82:85]
	v_mfma_f32_16x16x32_bf16 v[66:69], v[152:155], v[210:213], v[66:69]
	v_mfma_f32_16x16x32_bf16 v[66:69], v[156:159], v[214:217], v[66:69]
	v_mfma_f32_16x16x32_bf16 v[122:125], v[168:171], v[180:183], v[122:125]
	v_mfma_f32_16x16x32_bf16 v[122:125], v[172:175], v[184:187], v[122:125]
	v_mfma_f32_16x16x32_bf16 v[106:109], v[168:171], v[188:191], v[106:109]
	v_mfma_f32_16x16x32_bf16 v[106:109], v[172:175], v[192:195], v[106:109]
	v_mfma_f32_16x16x32_bf16 v[90:93], v[168:171], v[202:205], v[90:93]
	v_mfma_f32_16x16x32_bf16 v[90:93], v[172:175], v[206:209], v[90:93]
	v_mfma_f32_16x16x32_bf16 v[74:77], v[168:171], v[210:213], v[74:77]
	v_mfma_f32_16x16x32_bf16 v[74:77], v[172:175], v[214:217], v[74:77]
	s_setprio 0
	s_barrier
; #define PG8_STAGE(bufoff, gbase, voff) do { _Pragma("unroll") for (int _i = 0; _i < 2; ++_i) \
;         __builtin_amdgcn_global_load_lds((const unsigned*)((const char*)(gbase) + (voff)[_i]), (PG8_LAS unsigned*)(lds + (bufoff) + ldsw + _i * 8192), 16, 0, 0); } while (0)
; #define PG8_LDA(dst, b, h) do { _Pragma("unroll") for (int m = 0; m < 4; ++m) _Pragma("unroll") for (int k = 0; k < 2; ++k) dst[m][k] = *(const PG8_LAS bf16x8*)(lds + PG8_SA(b, h) + aoff + m * 2048 + k * 1024); } while (0)
; #define PG8_MMA(ai, bj, At, Bt) do { __builtin_amdgcn_s_setprio(1); _Pragma("unroll") for (int m = 0; m < 4; ++m) _Pragma("unroll") for (int n = 0; n < 2; ++n) _Pragma("unroll") for (int k = 0; k < 2; ++k) \
;         acc[ai][bj][m][n] = __builtin_amdgcn_mfma_f32_16x16x32_bf16(Bt[n][k], At[m][k], acc[ai][bj][m][n], 0, 0, 0); __builtin_amdgcn_s_setprio(0); } while (0)
; #define PG8_WAIT_V(n) asm volatile("s_waitcnt vmcnt(" #n ")" ::: "memory")
; #define PG8_WAIT_L(n) asm volatile("s_waitcnt lgkmcnt(" #n ")" ::: "memory")
; #define PG8_BAR __builtin_amdgcn_s_barrier()
; #define PG8_SCHED __builtin_amdgcn_sched_barrier(0)
; template <class Epi, class Sched, bool ALIGN_EPI = false, bool SP2 = false>
; __device__ __forceinline__ void gemm_phase(PG8_LAS unsigned char* lds, const Gemm g, const Sched& S, const Epi& E) {
;     ...
;             PG8_LDA(At, 1, 1); PG8_STAGE(PG8_SB(1, 0), b3, voffB); PG8_STAGE(PG8_SB(1, 1), b3 + hstep, voffB); PG8_STAGE(PG8_SA(1, 0), a3, voffA);
;             PG8_WAIT_V(8); PG8_WAIT_L(0); PG8_BAR; PG8_MMA(1, 0, At, B0); PG8_MMA(1, 1, At, B1); PG8_BAR; PG8_SCHED;
;     ...
;         if constexpr (ALIGN_EPI) { if (wr == 0) PG8_BAR; }
	s_add_i32 s18, s18, s91
	v_lshl_add_u64 v[218:219], v[218:219], 0, s[30:31]
	s_mov_b32 m0, s18
	ds_read_b128 v[180:183], v178 offset:49152
	ds_read_b128 v[184:187], v178 offset:50176
	ds_read_b128 v[188:191], v178 offset:51200
	ds_read_b128 v[192:195], v178 offset:52224
	ds_read_b128 v[202:205], v178 offset:53248
	ds_read_b128 v[206:209], v178 offset:54272
	ds_read_b128 v[210:213], v178 offset:55296
	ds_read_b128 v[214:217], v178 offset:56320
	global_load_lds_dwordx4 v[218:219], off
	s_add_i32 m0, s18, 0x2000
	s_add_u32 s38, s44, 0x40080
	v_lshl_add_u64 v[218:219], v[220:221], 0, s[30:31]
	s_addc_u32 s39, s45, 0
	s_add_i32 s18, vcc_lo, s91
	global_load_lds_dwordx4 v[218:219], off
	v_lshl_add_u64 v[218:219], s[38:39], 0, v[134:135]
	s_mov_b32 m0, s18
	s_nop 0
	global_load_lds_dwordx4 v[218:219], off
	v_lshl_add_u64 v[218:219], s[38:39], 0, v[130:131]
	s_add_i32 m0, s18, 0x2000
	s_nop 0
	global_load_lds_dwordx4 v[218:219], off
	v_lshl_add_u64 v[218:219], v[222:223], 0, s[30:31]
	s_mov_b32 m0, s7
	s_nop 0
	global_load_lds_dwordx4 v[218:219], off
	v_lshl_add_u64 v[218:219], v[224:225], 0, s[30:31]
	s_mov_b32 m0, s96
	s_nop 0
	global_load_lds_dwordx4 v[218:219], off
	s_waitcnt vmcnt(8)
	s_waitcnt lgkmcnt(0)
	s_barrier
	s_setprio 1
	s_waitcnt lgkmcnt(0)
	v_mfma_f32_16x16x32_bf16 v[54:57], v[144:147], v[180:183], v[54:57]
	v_mfma_f32_16x16x32_bf16 v[54:57], v[148:151], v[184:187], v[54:57]
	v_mfma_f32_16x16x32_bf16 v[38:41], v[144:147], v[188:191], v[38:41]
	v_mfma_f32_16x16x32_bf16 v[38:41], v[148:151], v[192:195], v[38:41]
	v_mfma_f32_16x16x32_bf16 v[22:25], v[144:147], v[202:205], v[22:25]
	v_mfma_f32_16x16x32_bf16 v[22:25], v[148:151], v[206:209], v[22:25]
	v_mfma_f32_16x16x32_bf16 v[6:9], v[144:147], v[210:213], v[6:9]
	v_mfma_f32_16x16x32_bf16 v[6:9], v[148:151], v[214:217], v[6:9]
	v_mfma_f32_16x16x32_bf16 v[62:65], v[160:163], v[180:183], v[62:65]
	v_mfma_f32_16x16x32_bf16 v[62:65], v[164:167], v[184:187], v[62:65]
	v_mfma_f32_16x16x32_bf16 v[46:49], v[160:163], v[188:191], v[46:49]
	v_mfma_f32_16x16x32_bf16 v[46:49], v[164:167], v[192:195], v[46:49]
	v_mfma_f32_16x16x32_bf16 v[30:33], v[160:163], v[202:205], v[30:33]
	v_mfma_f32_16x16x32_bf16 v[30:33], v[164:167], v[206:209], v[30:33]
	v_mfma_f32_16x16x32_bf16 v[10:13], v[160:163], v[210:213], v[10:13]
	v_mfma_f32_16x16x32_bf16 v[10:13], v[164:167], v[214:217], v[10:13]
	v_mfma_f32_16x16x32_bf16 v[50:53], v[152:155], v[180:183], v[50:53]
	v_mfma_f32_16x16x32_bf16 v[50:53], v[156:159], v[184:187], v[50:53]
	v_mfma_f32_16x16x32_bf16 v[34:37], v[152:155], v[188:191], v[34:37]
	v_mfma_f32_16x16x32_bf16 v[34:37], v[156:159], v[192:195], v[34:37]
	v_mfma_f32_16x16x32_bf16 v[18:21], v[152:155], v[202:205], v[18:21]
	v_mfma_f32_16x16x32_bf16 v[18:21], v[156:159], v[206:209], v[18:21]
	v_mfma_f32_16x16x32_bf16 v[2:5], v[152:155], v[210:213], v[2:5]
	v_mfma_f32_16x16x32_bf16 v[2:5], v[156:159], v[214:217], v[2:5]
	v_mfma_f32_16x16x32_bf16 v[58:61], v[168:171], v[180:183], v[58:61]
	v_mfma_f32_16x16x32_bf16 v[58:61], v[172:175], v[184:187], v[58:61]
	v_mfma_f32_16x16x32_bf16 v[42:45], v[168:171], v[188:191], v[42:45]
	v_mfma_f32_16x16x32_bf16 v[42:45], v[172:175], v[192:195], v[42:45]
	v_mfma_f32_16x16x32_bf16 v[26:29], v[168:171], v[202:205], v[26:29]
	v_mfma_f32_16x16x32_bf16 v[26:29], v[172:175], v[206:209], v[26:29]
	v_mfma_f32_16x16x32_bf16 v[14:17], v[168:171], v[210:213], v[14:17]
	v_mfma_f32_16x16x32_bf16 v[14:17], v[172:175], v[214:217], v[14:17]
	s_setprio 0
	s_barrier
	s_add_i32 s85, s85, 2
	s_add_u32 s46, s46, 0x100
	s_addc_u32 s47, s47, 0
	s_add_u32 s83, s83, 0x100
	s_addc_u32 s84, s84, 0
	s_cmp_gt_u32 s85, 13
	s_cbranch_scc0 .LBB0_132
	s_and_b64 vcc, exec, s[10:11]
	s_cbranch_vccz .LBB0_135
	s_barrier

; #define PG8_STAGE(bufoff, gbase, voff) do { _Pragma("unroll") for (int _i = 0; _i < 2; ++_i) \
;         __builtin_amdgcn_global_load_lds((const unsigned*)((const char*)(gbase) + (voff)[_i]), (PG8_LAS unsigned*)(lds + (bufoff) + ldsw + _i * 8192), 16, 0, 0); } while (0)
; #define PG8_LDA(dst, b, h) do { _Pragma("unroll") for (int m = 0; m < 4; ++m) _Pragma("unroll") for (int k = 0; k < 2; ++k) dst[m][k] = *(const PG8_LAS bf16x8*)(lds + PG8_SA(b, h) + aoff + m * 2048 + k * 1024); } while (0)
; #define PG8_LDB(dst, b, h) do { _Pragma("unroll") for (int n = 0; n < 2; ++n) _Pragma("unroll") for (int k = 0; k < 2; ++k) dst[n][k] = *(const PG8_LAS bf16x8*)(lds + PG8_SB(b, h) + boff + n * 2048 + k * 1024); } while (0)
; #define PG8_MMA(ai, bj, At, Bt) do { __builtin_amdgcn_s_setprio(1); _Pragma("unroll") for (int m = 0; m < 4; ++m) _Pragma("unroll") for (int n = 0; n < 2; ++n) _Pragma("unroll") for (int k = 0; k < 2; ++k) \
;         acc[ai][bj][m][n] = __builtin_amdgcn_mfma_f32_16x16x32_bf16(Bt[n][k], At[m][k], acc[ai][bj][m][n], 0, 0, 0); __builtin_amdgcn_s_setprio(0); } while (0)
; #define PG8_WAIT_V(n) asm volatile("s_waitcnt vmcnt(" #n ")" ::: "memory")
; #define PG8_BAR __builtin_amdgcn_s_barrier()
; template <class Epi, class Sched, bool ALIGN_EPI = false, bool SP2 = false>
; __device__ __forceinline__ void gemm_phase(PG8_LAS unsigned char* lds, const Gemm g, const Sched& S, const Epi& E) {
;     ...
;         for (int t = 0; t < nt; t += 2) {
;             const bool last = (t == nt - 2);
;             const char* a1 = cA + (size_t)(t + 1) * kstep;
;             const char* a2 = last ? nA : cA + (size_t)(t + 2) * kstep; const char* b2 = last ? nB : cB + (size_t)(t + 2) * kstep;
;             const char* a3 = a2 + kstep; const char* b3 = b2 + kstep;
;             if (last && has_next) S.a_ready(nxt);
;             if constexpr (SP2) {
;             PG8_LDB(B0, 0, 0); PG8_LDB(B1, 0, 1); PG8_SCHED; PG8_LDA(At, 0, 0); PG8_STAGE(PG8_SA(1, 1), a1 + hstep, voffA);
;             PG8_WAIT_V(8); PG8_WAIT_L(0); PG8_BAR; PG8_MMA(0, 0, At, B0); PG8_MMA(0, 1, At, B1); PG8_BAR; PG8_SCHED;
;             PG8_LDA(At, 0, 1); PG8_STAGE(PG8_SB(0, 0), b2, voffB); PG8_STAGE(PG8_SB(0, 1), b2 + hstep, voffB); PG8_STAGE(PG8_SA(0, 0), a2, voffA);
;             PG8_WAIT_V(8); PG8_WAIT_L(0); PG8_BAR; PG8_MMA(1, 0, At, B0); PG8_MMA(1, 1, At, B1); PG8_BAR; PG8_SCHED;
.LBB0_220:
	s_add_u32 s18, s60, 0xfffc0080
	s_addc_u32 s38, s61, -1
	s_add_i32 s39, 0, 0x10000
	s_cmp_eq_u32 s82, 12
	s_cselect_b32 s65, s47, s38
	s_cselect_b32 s64, s78, s18
	v_add_u32_e32 v145, s39, v141
	s_cselect_b32 s57, s49, s81
	s_cselect_b32 s56, s79, s80
	s_add_i32 s18, 0, 0x14000
	ds_read_b128 v[146:149], v145
	ds_read_b128 v[150:153], v145 offset:1024
	ds_read_b128 v[154:157], v145 offset:2048
	ds_read_b128 v[158:161], v145 offset:3072
	v_add_u32_e32 v145, s18, v141
	ds_read_b128 v[162:165], v145
	ds_read_b128 v[166:169], v145 offset:1024
	ds_read_b128 v[170:173], v145 offset:2048
	ds_read_b128 v[174:177], v145 offset:3072
	v_lshl_add_u64 v[194:195], s[60:61], 0, v[136:137]
	s_add_i32 m0, s29, 0xc000
	ds_read_b128 v[178:181], v144
	ds_read_b128 v[182:185], v144 offset:1024
	ds_read_b128 v[186:189], v144 offset:2048
	ds_read_b128 v[190:193], v144 offset:3072
	ds_read_b128 v[202:205], v144 offset:4096
	ds_read_b128 v[206:209], v144 offset:5120
	ds_read_b128 v[210:213], v144 offset:6144
	ds_read_b128 v[214:217], v144 offset:7168
	global_load_lds_dwordx4 v[194:195], off
	v_lshl_add_u64 v[194:195], s[60:61], 0, v[138:139]
	s_add_i32 m0, s29, 0xe000
	s_nop 0
	global_load_lds_dwordx4 v[194:195], off
	s_waitcnt vmcnt(8)
	s_waitcnt lgkmcnt(0)
	s_barrier
	s_setprio 1
	s_waitcnt lgkmcnt(0)
	v_mfma_f32_16x16x32_bf16 v[114:117], v[146:149], v[178:181], v[114:117]
	v_mfma_f32_16x16x32_bf16 v[114:117], v[150:153], v[182:185], v[114:117]
	v_mfma_f32_16x16x32_bf16 v[98:101], v[146:149], v[186:189], v[98:101]
	v_mfma_f32_16x16x32_bf16 v[98:101], v[150:153], v[190:193], v[98:101]
	v_mfma_f32_16x16x32_bf16 v[82:85], v[146:149], v[202:205], v[82:85]
	v_mfma_f32_16x16x32_bf16 v[82:85], v[150:153], v[206:209], v[82:85]
	v_mfma_f32_16x16x32_bf16 v[66:69], v[146:149], v[210:213], v[66:69]
	v_mfma_f32_16x16x32_bf16 v[66:69], v[150:153], v[214:217], v[66:69]
	v_mfma_f32_16x16x32_bf16 v[122:125], v[162:165], v[178:181], v[122:125]
	v_mfma_f32_16x16x32_bf16 v[122:125], v[166:169], v[182:185], v[122:125]
	v_mfma_f32_16x16x32_bf16 v[106:109], v[162:165], v[186:189], v[106:109]
	v_mfma_f32_16x16x32_bf16 v[106:109], v[166:169], v[190:193], v[106:109]
	v_mfma_f32_16x16x32_bf16 v[90:93], v[162:165], v[202:205], v[90:93]
	v_mfma_f32_16x16x32_bf16 v[90:93], v[166:169], v[206:209], v[90:93]
	v_mfma_f32_16x16x32_bf16 v[74:77], v[162:165], v[210:213], v[74:77]
	v_mfma_f32_16x16x32_bf16 v[74:77], v[166:169], v[214:217], v[74:77]
	v_mfma_f32_16x16x32_bf16 v[118:121], v[154:157], v[178:181], v[118:121]
	v_mfma_f32_16x16x32_bf16 v[118:121], v[158:161], v[182:185], v[118:121]
	v_mfma_f32_16x16x32_bf16 v[102:105], v[154:157], v[186:189], v[102:105]
	v_mfma_f32_16x16x32_bf16 v[102:105], v[158:161], v[190:193], v[102:105]
	v_mfma_f32_16x16x32_bf16 v[86:89], v[154:157], v[202:205], v[86:89]
	v_mfma_f32_16x16x32_bf16 v[86:89], v[158:161], v[206:209], v[86:89]
	v_mfma_f32_16x16x32_bf16 v[70:73], v[154:157], v[210:213], v[70:73]
	v_mfma_f32_16x16x32_bf16 v[70:73], v[158:161], v[214:217], v[70:73]
	v_mfma_f32_16x16x32_bf16 v[126:129], v[170:173], v[178:181], v[126:129]
	v_mfma_f32_16x16x32_bf16 v[126:129], v[174:177], v[182:185], v[126:129]
	v_mfma_f32_16x16x32_bf16 v[110:113], v[170:173], v[186:189], v[110:113]
	v_mfma_f32_16x16x32_bf16 v[110:113], v[174:177], v[190:193], v[110:113]
	v_mfma_f32_16x16x32_bf16 v[94:97], v[170:173], v[202:205], v[94:97]
	v_mfma_f32_16x16x32_bf16 v[94:97], v[174:177], v[206:209], v[94:97]
	v_mfma_f32_16x16x32_bf16 v[78:81], v[170:173], v[210:213], v[78:81]
	v_mfma_f32_16x16x32_bf16 v[78:81], v[174:177], v[214:217], v[78:81]
	s_setprio 0
	s_barrier
	s_add_i32 s38, s39, s27
	v_lshl_add_u64 v[194:195], s[56:57], 0, v[0:1]
	s_mov_b32 m0, s38
	ds_read_b128 v[178:181], v144 offset:16384
	ds_read_b128 v[182:185], v144 offset:17408
	ds_read_b128 v[186:189], v144 offset:18432
	ds_read_b128 v[190:193], v144 offset:19456
	ds_read_b128 v[202:205], v144 offset:20480
	ds_read_b128 v[206:209], v144 offset:21504
	ds_read_b128 v[210:213], v144 offset:22528
	ds_read_b128 v[214:217], v144 offset:23552
	global_load_lds_dwordx4 v[194:195], off
	s_add_i32 m0, s38, 0x2000
	s_add_u32 s38, s56, 0x40000
	v_lshl_add_u64 v[218:219], s[56:57], 0, v[130:131]
	s_addc_u32 s39, s57, 0
	s_add_i32 s18, s18, s27
	global_load_lds_dwordx4 v[218:219], off
	v_lshl_add_u64 v[220:221], s[38:39], 0, v[0:1]
	s_mov_b32 m0, s18
	v_lshl_add_u64 v[222:223], s[64:65], 0, v[132:133]
	global_load_lds_dwordx4 v[220:221], off
	v_lshl_add_u64 v[220:221], s[38:39], 0, v[130:131]
	s_add_i32 m0, s18, 0x2000
	s_nop 0
	global_load_lds_dwordx4 v[220:221], off
	v_lshl_add_u64 v[220:221], s[64:65], 0, v[134:135]
	s_mov_b32 m0, s29
	s_nop 0
	global_load_lds_dwordx4 v[220:221], off
	s_mov_b32 m0, s33
	s_nop 0
	global_load_lds_dwordx4 v[222:223], off
	s_waitcnt vmcnt(8)
	s_waitcnt lgkmcnt(0)
	s_barrier
; #define PG8_STAGE(bufoff, gbase, voff) do { _Pragma("unroll") for (int _i = 0; _i < 2; ++_i) \
;         __builtin_amdgcn_global_load_lds((const unsigned*)((const char*)(gbase) + (voff)[_i]), (PG8_LAS unsigned*)(lds + (bufoff) + ldsw + _i * 8192), 16, 0, 0); } while (0)
; #define PG8_LDA(dst, b, h) do { _Pragma("unroll") for (int m = 0; m < 4; ++m) _Pragma("unroll") for (int k = 0; k < 2; ++k) dst[m][k] = *(const PG8_LAS bf16x8*)(lds + PG8_SA(b, h) + aoff + m * 2048 + k * 1024); } while (0)
; #define PG8_LDB(dst, b, h) do { _Pragma("unroll") for (int n = 0; n < 2; ++n) _Pragma("unroll") for (int k = 0; k < 2; ++k) dst[n][k] = *(const PG8_LAS bf16x8*)(lds + PG8_SB(b, h) + boff + n * 2048 + k * 1024); } while (0)
; #define PG8_MMA(ai, bj, At, Bt) do { __builtin_amdgcn_s_setprio(1); _Pragma("unroll") for (int m = 0; m < 4; ++m) _Pragma("unroll") for (int n = 0; n < 2; ++n) _Pragma("unroll") for (int k = 0; k < 2; ++k) \
;         acc[ai][bj][m][n] = __builtin_amdgcn_mfma_f32_16x16x32_bf16(Bt[n][k], At[m][k], acc[ai][bj][m][n], 0, 0, 0); __builtin_amdgcn_s_setprio(0); } while (0)
; #define PG8_WAIT_V(n) asm volatile("s_waitcnt vmcnt(" #n ")" ::: "memory")
; #define PG8_WAIT_L(n) asm volatile("s_waitcnt lgkmcnt(" #n ")" ::: "memory")
; #define PG8_BAR __builtin_amdgcn_s_barrier()
; #define PG8_SCHED __builtin_amdgcn_sched_barrier(0)
; template <class Epi, class Sched, bool ALIGN_EPI = false, bool SP2 = false>
; __device__ __forceinline__ void gemm_phase(PG8_LAS unsigned char* lds, const Gemm g, const Sched& S, const Epi& E) {
;     ...
;             PG8_WAIT_V(8); PG8_WAIT_L(0); PG8_BAR; PG8_MMA(1, 0, At, B0); PG8_MMA(1, 1, At, B1); PG8_BAR; PG8_SCHED;
;             PG8_LDB(B0, 1, 0); PG8_LDB(B1, 1, 1); PG8_SCHED; PG8_LDA(At, 1, 0); PG8_STAGE(PG8_SA(0, 1), a2 + hstep, voffA);
;             PG8_WAIT_V(8); PG8_WAIT_L(0); PG8_BAR; PG8_MMA(0, 0, At, B0); PG8_MMA(0, 1, At, B1); PG8_BAR; PG8_SCHED;
	s_setprio 1
	s_waitcnt lgkmcnt(0)
	v_mfma_f32_16x16x32_bf16 v[50:53], v[146:149], v[178:181], v[50:53]
	v_mfma_f32_16x16x32_bf16 v[50:53], v[150:153], v[182:185], v[50:53]
	v_mfma_f32_16x16x32_bf16 v[34:37], v[146:149], v[186:189], v[34:37]
	v_mfma_f32_16x16x32_bf16 v[34:37], v[150:153], v[190:193], v[34:37]
	v_mfma_f32_16x16x32_bf16 v[18:21], v[146:149], v[202:205], v[18:21]
	v_mfma_f32_16x16x32_bf16 v[18:21], v[150:153], v[206:209], v[18:21]
	v_mfma_f32_16x16x32_bf16 v[2:5], v[146:149], v[210:213], v[2:5]
	v_mfma_f32_16x16x32_bf16 v[2:5], v[150:153], v[214:217], v[2:5]
	v_mfma_f32_16x16x32_bf16 v[58:61], v[162:165], v[178:181], v[58:61]
	v_mfma_f32_16x16x32_bf16 v[58:61], v[166:169], v[182:185], v[58:61]
	v_mfma_f32_16x16x32_bf16 v[42:45], v[162:165], v[186:189], v[42:45]
	v_mfma_f32_16x16x32_bf16 v[42:45], v[166:169], v[190:193], v[42:45]
	v_mfma_f32_16x16x32_bf16 v[26:29], v[162:165], v[202:205], v[26:29]
	v_mfma_f32_16x16x32_bf16 v[26:29], v[166:169], v[206:209], v[26:29]
	v_mfma_f32_16x16x32_bf16 v[10:13], v[162:165], v[210:213], v[10:13]
	v_mfma_f32_16x16x32_bf16 v[10:13], v[166:169], v[214:217], v[10:13]
	v_mfma_f32_16x16x32_bf16 v[54:57], v[154:157], v[178:181], v[54:57]
	v_mfma_f32_16x16x32_bf16 v[54:57], v[158:161], v[182:185], v[54:57]
	v_mfma_f32_16x16x32_bf16 v[38:41], v[154:157], v[186:189], v[38:41]
	v_mfma_f32_16x16x32_bf16 v[38:41], v[158:161], v[190:193], v[38:41]
	v_mfma_f32_16x16x32_bf16 v[22:25], v[154:157], v[202:205], v[22:25]
	v_mfma_f32_16x16x32_bf16 v[22:25], v[158:161], v[206:209], v[22:25]
	v_mfma_f32_16x16x32_bf16 v[6:9], v[154:157], v[210:213], v[6:9]
	v_mfma_f32_16x16x32_bf16 v[6:9], v[158:161], v[214:217], v[6:9]
	v_mfma_f32_16x16x32_bf16 v[62:65], v[170:173], v[178:181], v[62:65]
	v_mfma_f32_16x16x32_bf16 v[62:65], v[174:177], v[182:185], v[62:65]
	v_mfma_f32_16x16x32_bf16 v[46:49], v[170:173], v[186:189], v[46:49]
	v_mfma_f32_16x16x32_bf16 v[46:49], v[174:177], v[190:193], v[46:49]
	v_mfma_f32_16x16x32_bf16 v[30:33], v[170:173], v[202:205], v[30:33]
	v_mfma_f32_16x16x32_bf16 v[30:33], v[174:177], v[206:209], v[30:33]
	v_mfma_f32_16x16x32_bf16 v[14:17], v[170:173], v[210:213], v[14:17]
	v_mfma_f32_16x16x32_bf16 v[14:17], v[174:177], v[214:217], v[14:17]
	s_setprio 0
	s_barrier
	s_add_i32 s18, 0, 0x18000
	v_add_u32_e32 v145, s18, v141
	s_add_i32 s83, 0, 0x1c000
	ds_read_b128 v[146:149], v145
	ds_read_b128 v[150:153], v145 offset:1024
	ds_read_b128 v[154:157], v145 offset:2048
	ds_read_b128 v[158:161], v145 offset:3072
	v_add_u32_e32 v145, s83, v141
	ds_read_b128 v[162:165], v145
	ds_read_b128 v[166:169], v145 offset:1024
	ds_read_b128 v[170:173], v145 offset:2048
	ds_read_b128 v[174:177], v145 offset:3072
	s_add_u32 s38, s64, 0x40000
	s_addc_u32 s39, s65, 0
	s_mov_b32 m0, s58
	v_lshl_add_u64 v[224:225], s[38:39], 0, v[134:135]
	ds_read_b128 v[178:181], v144 offset:32768
	ds_read_b128 v[182:185], v144 offset:33792
	ds_read_b128 v[186:189], v144 offset:34816
	ds_read_b128 v[190:193], v144 offset:35840
	ds_read_b128 v[202:205], v144 offset:36864
	ds_read_b128 v[206:209], v144 offset:37888
	ds_read_b128 v[210:213], v144 offset:38912
	ds_read_b128 v[214:217], v144 offset:39936
	global_load_lds_dwordx4 v[224:225], off
	v_lshl_add_u64 v[224:225], s[38:39], 0, v[132:133]
	s_mov_b32 m0, s69
	s_nop 0
	global_load_lds_dwordx4 v[224:225], off
	s_waitcnt vmcnt(8)
	s_waitcnt lgkmcnt(0)
	s_barrier
	s_setprio 1
	s_waitcnt lgkmcnt(0)
	v_mfma_f32_16x16x32_bf16 v[114:117], v[146:149], v[178:181], v[114:117]
	v_mfma_f32_16x16x32_bf16 v[114:117], v[150:153], v[182:185], v[114:117]
	v_mfma_f32_16x16x32_bf16 v[98:101], v[146:149], v[186:189], v[98:101]
	v_mfma_f32_16x16x32_bf16 v[98:101], v[150:153], v[190:193], v[98:101]
	v_mfma_f32_16x16x32_bf16 v[82:85], v[146:149], v[202:205], v[82:85]
	v_mfma_f32_16x16x32_bf16 v[82:85], v[150:153], v[206:209], v[82:85]
	v_mfma_f32_16x16x32_bf16 v[66:69], v[146:149], v[210:213], v[66:69]
	v_mfma_f32_16x16x32_bf16 v[66:69], v[150:153], v[214:217], v[66:69]
	v_mfma_f32_16x16x32_bf16 v[122:125], v[162:165], v[178:181], v[122:125]
	v_mfma_f32_16x16x32_bf16 v[122:125], v[166:169], v[182:185], v[122:125]
	v_mfma_f32_16x16x32_bf16 v[106:109], v[162:165], v[186:189], v[106:109]
	v_mfma_f32_16x16x32_bf16 v[106:109], v[166:169], v[190:193], v[106:109]
	v_mfma_f32_16x16x32_bf16 v[90:93], v[162:165], v[202:205], v[90:93]
	v_mfma_f32_16x16x32_bf16 v[90:93], v[166:169], v[206:209], v[90:93]
	v_mfma_f32_16x16x32_bf16 v[74:77], v[162:165], v[210:213], v[74:77]
	v_mfma_f32_16x16x32_bf16 v[74:77], v[166:169], v[214:217], v[74:77]
	v_mfma_f32_16x16x32_bf16 v[118:121], v[154:157], v[178:181], v[118:121]
	v_mfma_f32_16x16x32_bf16 v[118:121], v[158:161], v[182:185], v[118:121]
	v_mfma_f32_16x16x32_bf16 v[102:105], v[154:157], v[186:189], v[102:105]
	v_mfma_f32_16x16x32_bf16 v[102:105], v[158:161], v[190:193], v[102:105]
	v_mfma_f32_16x16x32_bf16 v[86:89], v[154:157], v[202:205], v[86:89]
	v_mfma_f32_16x16x32_bf16 v[86:89], v[158:161], v[206:209], v[86:89]
	v_mfma_f32_16x16x32_bf16 v[70:73], v[154:157], v[210:213], v[70:73]
	v_mfma_f32_16x16x32_bf16 v[70:73], v[158:161], v[214:217], v[70:73]
	v_mfma_f32_16x16x32_bf16 v[126:129], v[170:173], v[178:181], v[126:129]
	v_mfma_f32_16x16x32_bf16 v[126:129], v[174:177], v[182:185], v[126:129]
	v_mfma_f32_16x16x32_bf16 v[110:113], v[170:173], v[186:189], v[110:113]
	v_mfma_f32_16x16x32_bf16 v[110:113], v[174:177], v[190:193], v[110:113]
	v_mfma_f32_16x16x32_bf16 v[94:97], v[170:173], v[202:205], v[94:97]
	v_mfma_f32_16x16x32_bf16 v[94:97], v[174:177], v[206:209], v[94:97]
	v_mfma_f32_16x16x32_bf16 v[78:81], v[170:173], v[210:213], v[78:81]
	v_mfma_f32_16x16x32_bf16 v[78:81], v[174:177], v[214:217], v[78:81]
	s_setprio 0
	s_barrier
; #define PG8_STAGE(bufoff, gbase, voff) do { _Pragma("unroll") for (int _i = 0; _i < 2; ++_i) \
;         __builtin_amdgcn_global_load_lds((const unsigned*)((const char*)(gbase) + (voff)[_i]), (PG8_LAS unsigned*)(lds + (bufoff) + ldsw + _i * 8192), 16, 0, 0); } while (0)
; #define PG8_LDA(dst, b, h) do { _Pragma("unroll") for (int m = 0; m < 4; ++m) _Pragma("unroll") for (int k = 0; k < 2; ++k) dst[m][k] = *(const PG8_LAS bf16x8*)(lds + PG8_SA(b, h) + aoff + m * 2048 + k * 1024); } while (0)
; #define PG8_MMA(ai, bj, At, Bt) do { __builtin_amdgcn_s_setprio(1); _Pragma("unroll") for (int m = 0; m < 4; ++m) _Pragma("unroll") for (int n = 0; n < 2; ++n) _Pragma("unroll") for (int k = 0; k < 2; ++k) \
;         acc[ai][bj][m][n] = __builtin_amdgcn_mfma_f32_16x16x32_bf16(Bt[n][k], At[m][k], acc[ai][bj][m][n], 0, 0, 0); __builtin_amdgcn_s_setprio(0); } while (0)
; #define PG8_WAIT_V(n) asm volatile("s_waitcnt vmcnt(" #n ")" ::: "memory")
; #define PG8_WAIT_L(n) asm volatile("s_waitcnt lgkmcnt(" #n ")" ::: "memory")
; #define PG8_BAR __builtin_amdgcn_s_barrier()
; #define PG8_SCHED __builtin_amdgcn_sched_barrier(0)
; template <class Epi, class Sched, bool ALIGN_EPI = false, bool SP2 = false>
; __device__ __forceinline__ void gemm_phase(PG8_LAS unsigned char* lds, const Gemm g, const Sched& S, const Epi& E) {
;     ...
;             PG8_LDA(At, 1, 1); PG8_STAGE(PG8_SB(1, 0), b3, voffB); PG8_STAGE(PG8_SB(1, 1), b3 + hstep, voffB); PG8_STAGE(PG8_SA(1, 0), a3, voffA);
;             PG8_WAIT_V(8); PG8_WAIT_L(0); PG8_BAR; PG8_MMA(1, 0, At, B0); PG8_MMA(1, 1, At, B1); PG8_BAR; PG8_SCHED;
;     ...
;         if constexpr (ALIGN_EPI) { if (wr == 0) PG8_BAR; }
	s_add_i32 s18, s18, s27
	v_lshl_add_u64 v[194:195], v[194:195], 0, s[30:31]
	s_mov_b32 m0, s18
	ds_read_b128 v[178:181], v144 offset:49152
	ds_read_b128 v[182:185], v144 offset:50176
	ds_read_b128 v[186:189], v144 offset:51200
	ds_read_b128 v[190:193], v144 offset:52224
	ds_read_b128 v[202:205], v144 offset:53248
	ds_read_b128 v[206:209], v144 offset:54272
	ds_read_b128 v[210:213], v144 offset:55296
	ds_read_b128 v[214:217], v144 offset:56320
	global_load_lds_dwordx4 v[194:195], off
	s_add_i32 m0, s18, 0x2000
	s_add_u32 s38, s56, 0x40080
	v_lshl_add_u64 v[194:195], v[218:219], 0, s[30:31]
	s_addc_u32 s39, s57, 0
	s_add_i32 s18, s83, s27
	global_load_lds_dwordx4 v[194:195], off
	v_lshl_add_u64 v[194:195], s[38:39], 0, v[0:1]
	s_mov_b32 m0, s18
	s_nop 0
	global_load_lds_dwordx4 v[194:195], off
	v_lshl_add_u64 v[194:195], s[38:39], 0, v[130:131]
	s_add_i32 m0, s18, 0x2000
	s_nop 0
	global_load_lds_dwordx4 v[194:195], off
	v_lshl_add_u64 v[194:195], v[220:221], 0, s[30:31]
	s_mov_b32 m0, s71
	s_nop 0
	global_load_lds_dwordx4 v[194:195], off
	v_lshl_add_u64 v[194:195], v[222:223], 0, s[30:31]
	s_mov_b32 m0, s72
	s_nop 0
	global_load_lds_dwordx4 v[194:195], off
	s_waitcnt vmcnt(8)
	s_waitcnt lgkmcnt(0)
	s_barrier
	s_setprio 1
	s_waitcnt lgkmcnt(0)
	v_mfma_f32_16x16x32_bf16 v[50:53], v[146:149], v[178:181], v[50:53]
	v_mfma_f32_16x16x32_bf16 v[50:53], v[150:153], v[182:185], v[50:53]
	v_mfma_f32_16x16x32_bf16 v[34:37], v[146:149], v[186:189], v[34:37]
	v_mfma_f32_16x16x32_bf16 v[34:37], v[150:153], v[190:193], v[34:37]
	v_mfma_f32_16x16x32_bf16 v[18:21], v[146:149], v[202:205], v[18:21]
	v_mfma_f32_16x16x32_bf16 v[18:21], v[150:153], v[206:209], v[18:21]
	v_mfma_f32_16x16x32_bf16 v[2:5], v[146:149], v[210:213], v[2:5]
	v_mfma_f32_16x16x32_bf16 v[2:5], v[150:153], v[214:217], v[2:5]
	v_mfma_f32_16x16x32_bf16 v[58:61], v[162:165], v[178:181], v[58:61]
	v_mfma_f32_16x16x32_bf16 v[58:61], v[166:169], v[182:185], v[58:61]
	v_mfma_f32_16x16x32_bf16 v[42:45], v[162:165], v[186:189], v[42:45]
	v_mfma_f32_16x16x32_bf16 v[42:45], v[166:169], v[190:193], v[42:45]
	v_mfma_f32_16x16x32_bf16 v[26:29], v[162:165], v[202:205], v[26:29]
	v_mfma_f32_16x16x32_bf16 v[26:29], v[166:169], v[206:209], v[26:29]
	v_mfma_f32_16x16x32_bf16 v[10:13], v[162:165], v[210:213], v[10:13]
	v_mfma_f32_16x16x32_bf16 v[10:13], v[166:169], v[214:217], v[10:13]
	v_mfma_f32_16x16x32_bf16 v[54:57], v[154:157], v[178:181], v[54:57]
	v_mfma_f32_16x16x32_bf16 v[54:57], v[158:161], v[182:185], v[54:57]
	v_mfma_f32_16x16x32_bf16 v[38:41], v[154:157], v[186:189], v[38:41]
	v_mfma_f32_16x16x32_bf16 v[38:41], v[158:161], v[190:193], v[38:41]
	v_mfma_f32_16x16x32_bf16 v[22:25], v[154:157], v[202:205], v[22:25]
	v_mfma_f32_16x16x32_bf16 v[22:25], v[158:161], v[206:209], v[22:25]
	v_mfma_f32_16x16x32_bf16 v[6:9], v[154:157], v[210:213], v[6:9]
	v_mfma_f32_16x16x32_bf16 v[6:9], v[158:161], v[214:217], v[6:9]
	v_mfma_f32_16x16x32_bf16 v[62:65], v[170:173], v[178:181], v[62:65]
	v_mfma_f32_16x16x32_bf16 v[62:65], v[174:177], v[182:185], v[62:65]
	v_mfma_f32_16x16x32_bf16 v[46:49], v[170:173], v[186:189], v[46:49]
	v_mfma_f32_16x16x32_bf16 v[46:49], v[174:177], v[190:193], v[46:49]
	v_mfma_f32_16x16x32_bf16 v[30:33], v[170:173], v[202:205], v[30:33]
	v_mfma_f32_16x16x32_bf16 v[30:33], v[174:177], v[206:209], v[30:33]
	v_mfma_f32_16x16x32_bf16 v[14:17], v[170:173], v[210:213], v[14:17]
	v_mfma_f32_16x16x32_bf16 v[14:17], v[174:177], v[214:217], v[14:17]
	s_setprio 0
	s_barrier
	s_add_i32 s82, s82, 2
	s_add_u32 s60, s60, 0x100
	s_addc_u32 s61, s61, 0
	s_add_u32 s80, s80, 0x100
	s_addc_u32 s81, s81, 0
	s_cmp_gt_u32 s82, 13
	s_cbranch_scc0 .LBB0_220
	s_and_b64 vcc, exec, s[44:45]
	s_cbranch_vccz .LBB0_223
	s_barrier

; #define PG8_STAGE(bufoff, gbase, voff) do { _Pragma("unroll") for (int _i = 0; _i < 2; ++_i) \
;         __builtin_amdgcn_global_load_lds((const unsigned*)((const char*)(gbase) + (voff)[_i]), (PG8_LAS unsigned*)(lds + (bufoff) + ldsw + _i * 8192), 16, 0, 0); } while (0)
; #define PG8_LDA(dst, b, h) do { _Pragma("unroll") for (int m = 0; m < 4; ++m) _Pragma("unroll") for (int k = 0; k < 2; ++k) dst[m][k] = *(const PG8_LAS bf16x8*)(lds + PG8_SA(b, h) + aoff + m * 2048 + k * 1024); } while (0)
; #define PG8_LDB(dst, b, h) do { _Pragma("unroll") for (int n = 0; n < 2; ++n) _Pragma("unroll") for (int k = 0; k < 2; ++k) dst[n][k] = *(const PG8_LAS bf16x8*)(lds + PG8_SB(b, h) + boff + n * 2048 + k * 1024); } while (0)
; #define PG8_MMA(ai, bj, At, Bt) do { __builtin_amdgcn_s_setprio(1); _Pragma("unroll") for (int m = 0; m < 4; ++m) _Pragma("unroll") for (int n = 0; n < 2; ++n) _Pragma("unroll") for (int k = 0; k < 2; ++k) \
;         acc[ai][bj][m][n] = __builtin_amdgcn_mfma_f32_16x16x32_bf16(Bt[n][k], At[m][k], acc[ai][bj][m][n], 0, 0, 0); __builtin_amdgcn_s_setprio(0); } while (0)
; #define PG8_WAIT_V(n) asm volatile("s_waitcnt vmcnt(" #n ")" ::: "memory")
; #define PG8_BAR __builtin_amdgcn_s_barrier()
; template <class Epi, class Sched, bool ALIGN_EPI = false, bool SP2 = false>
; __device__ __forceinline__ void gemm_phase(PG8_LAS unsigned char* lds, const Gemm g, const Sched& S, const Epi& E) {
;     ...
;         for (int t = 0; t < nt; t += 2) {
;             const bool last = (t == nt - 2);
;             const char* a1 = cA + (size_t)(t + 1) * kstep;
;             const char* a2 = last ? nA : cA + (size_t)(t + 2) * kstep; const char* b2 = last ? nB : cB + (size_t)(t + 2) * kstep;
;             const char* a3 = a2 + kstep; const char* b3 = b2 + kstep;
;             if (last && has_next) S.a_ready(nxt);
;             if constexpr (SP2) {
;             PG8_LDB(B0, 0, 0); PG8_LDB(B1, 0, 1); PG8_SCHED; PG8_LDA(At, 0, 0); PG8_STAGE(PG8_SA(1, 1), a1 + hstep, voffA);
;             PG8_WAIT_V(8); PG8_WAIT_L(0); PG8_BAR; PG8_MMA(0, 0, At, B0); PG8_MMA(0, 1, At, B1); PG8_BAR; PG8_SCHED;
;             PG8_LDA(At, 0, 1); PG8_STAGE(PG8_SB(0, 0), b2, voffB); PG8_STAGE(PG8_SB(0, 1), b2 + hstep, voffB); PG8_STAGE(PG8_SA(0, 0), a2, voffA);
;             PG8_WAIT_V(8); PG8_WAIT_L(0); PG8_BAR; PG8_MMA(1, 0, At, B0); PG8_MMA(1, 1, At, B1); PG8_BAR; PG8_SCHED;
.LBB0_274:
	s_add_i32 vcc_lo, s46, 2
	s_add_u32 s38, s48, 0x80
	s_addc_u32 s39, s49, 0
	s_add_i32 vcc_hi, 0, 0x10000
	s_cmp_eq_u32 s99, s46
	s_cselect_b32 s47, s81, s39
	s_cselect_b32 s46, s80, s38
	s_cselect_b32 s39, s83, s51
	s_cselect_b32 s38, s82, s50
	s_add_i32 s18, 0, 0x14000
	v_add_u32_e32 v142, vcc_hi, v245
	v_add_u32_e32 v158, s18, v245
	ds_read_b128 v[110:113], v142
	ds_read_b128 v[118:121], v142 offset:1024
	ds_read_b128 v[138:141], v142 offset:2048
	ds_read_b128 v[142:145], v142 offset:3072
	ds_read_b128 v[146:149], v158
	ds_read_b128 v[150:153], v158 offset:1024
	ds_read_b128 v[154:157], v158 offset:2048
	ds_read_b128 v[158:161], v158 offset:3072
	v_lshl_add_u64 v[210:211], s[48:49], 0, v[206:207]
	s_add_i32 m0, s92, 0xc000
	ds_read_b128 v[162:165], v247
	ds_read_b128 v[166:169], v247 offset:1024
	ds_read_b128 v[170:173], v247 offset:2048
	ds_read_b128 v[174:177], v247 offset:3072
	ds_read_b128 v[178:181], v247 offset:4096
	ds_read_b128 v[182:185], v247 offset:5120
	ds_read_b128 v[186:189], v247 offset:6144
	ds_read_b128 v[190:193], v247 offset:7168
	global_load_lds_dwordx4 v[210:211], off
	v_lshl_add_u64 v[210:211], s[48:49], 0, v[208:209]
	s_add_i32 m0, s92, 0xe000
	s_nop 0
	global_load_lds_dwordx4 v[210:211], off
	s_waitcnt vmcnt(8)
	s_waitcnt lgkmcnt(0)
	s_barrier
	s_setprio 1
	s_waitcnt lgkmcnt(0)
	v_mfma_f32_16x16x32_bf16 v[130:133], v[110:113], v[162:165], v[130:133]
	v_mfma_f32_16x16x32_bf16 v[130:133], v[118:121], v[166:169], v[130:133]
	v_mfma_f32_16x16x32_bf16 v[114:117], v[110:113], v[170:173], v[114:117]
	v_mfma_f32_16x16x32_bf16 v[114:117], v[118:121], v[174:177], v[114:117]
	v_mfma_f32_16x16x32_bf16 v[94:97], v[110:113], v[178:181], v[94:97]
	v_mfma_f32_16x16x32_bf16 v[94:97], v[118:121], v[182:185], v[94:97]
	v_mfma_f32_16x16x32_bf16 v[78:81], v[110:113], v[186:189], v[78:81]
	v_mfma_f32_16x16x32_bf16 v[78:81], v[118:121], v[190:193], v[78:81]
	v_mfma_f32_16x16x32_bf16 v[126:129], v[146:149], v[162:165], v[126:129]
	v_mfma_f32_16x16x32_bf16 v[126:129], v[150:153], v[166:169], v[126:129]
	v_mfma_f32_16x16x32_bf16 v[102:105], v[146:149], v[170:173], v[102:105]
	v_mfma_f32_16x16x32_bf16 v[102:105], v[150:153], v[174:177], v[102:105]
	v_mfma_f32_16x16x32_bf16 v[86:89], v[146:149], v[178:181], v[86:89]
	v_mfma_f32_16x16x32_bf16 v[86:89], v[150:153], v[182:185], v[86:89]
	v_mfma_f32_16x16x32_bf16 v[70:73], v[146:149], v[186:189], v[70:73]
	v_mfma_f32_16x16x32_bf16 v[70:73], v[150:153], v[190:193], v[70:73]
	v_mfma_f32_16x16x32_bf16 v[134:137], v[138:141], v[162:165], v[134:137]
	v_mfma_f32_16x16x32_bf16 v[134:137], v[142:145], v[166:169], v[134:137]
	v_mfma_f32_16x16x32_bf16 v[106:109], v[138:141], v[170:173], v[106:109]
	v_mfma_f32_16x16x32_bf16 v[106:109], v[142:145], v[174:177], v[106:109]
	v_mfma_f32_16x16x32_bf16 v[90:93], v[138:141], v[178:181], v[90:93]
	v_mfma_f32_16x16x32_bf16 v[90:93], v[142:145], v[182:185], v[90:93]
	v_mfma_f32_16x16x32_bf16 v[74:77], v[138:141], v[186:189], v[74:77]
	v_mfma_f32_16x16x32_bf16 v[74:77], v[142:145], v[190:193], v[74:77]
	v_mfma_f32_16x16x32_bf16 v[122:125], v[154:157], v[162:165], v[122:125]
	v_mfma_f32_16x16x32_bf16 v[122:125], v[158:161], v[166:169], v[122:125]
	v_mfma_f32_16x16x32_bf16 v[98:101], v[154:157], v[170:173], v[98:101]
	v_mfma_f32_16x16x32_bf16 v[98:101], v[158:161], v[174:177], v[98:101]
	v_mfma_f32_16x16x32_bf16 v[82:85], v[154:157], v[178:181], v[82:85]
	v_mfma_f32_16x16x32_bf16 v[82:85], v[158:161], v[182:185], v[82:85]
	v_mfma_f32_16x16x32_bf16 v[66:69], v[154:157], v[186:189], v[66:69]
	v_mfma_f32_16x16x32_bf16 v[66:69], v[158:161], v[190:193], v[66:69]
	s_setprio 0
	s_barrier
	s_add_i32 vcc_hi, vcc_hi, s6
	v_lshl_add_u64 v[210:211], s[38:39], 0, v[0:1]
	s_mov_b32 m0, vcc_hi
	ds_read_b128 v[162:165], v247 offset:16384
	ds_read_b128 v[166:169], v247 offset:17408
	ds_read_b128 v[170:173], v247 offset:18432
	ds_read_b128 v[174:177], v247 offset:19456
	ds_read_b128 v[178:181], v247 offset:20480
	ds_read_b128 v[182:185], v247 offset:21504
	ds_read_b128 v[186:189], v247 offset:22528
	ds_read_b128 v[190:193], v247 offset:23552
	global_load_lds_dwordx4 v[210:211], off
	s_add_i32 m0, vcc_hi, 0x2000
	v_lshl_add_u64 v[212:213], s[38:39], 0, v[204:205]
	s_add_u32 s38, s38, s58
	s_addc_u32 s39, s39, 0
	s_add_i32 s18, s18, s6
	global_load_lds_dwordx4 v[212:213], off
	v_lshl_add_u64 v[214:215], s[38:39], 0, v[0:1]
	s_mov_b32 m0, s18
	v_lshl_add_u64 v[216:217], s[38:39], 0, v[204:205]
	global_load_lds_dwordx4 v[214:215], off
	s_add_i32 m0, s18, 0x2000
	v_lshl_add_u64 v[218:219], s[46:47], 0, v[194:195]
	global_load_lds_dwordx4 v[216:217], off
	s_mov_b32 m0, s92
	v_lshl_add_u64 v[220:221], s[46:47], 0, v[202:203]
	global_load_lds_dwordx4 v[218:219], off
	s_mov_b32 m0, s93
	s_nop 0
	global_load_lds_dwordx4 v[220:221], off
	s_waitcnt vmcnt(8)
	s_waitcnt lgkmcnt(0)
	s_barrier
; #define PG8_STAGE(bufoff, gbase, voff) do { _Pragma("unroll") for (int _i = 0; _i < 2; ++_i) \
;         __builtin_amdgcn_global_load_lds((const unsigned*)((const char*)(gbase) + (voff)[_i]), (PG8_LAS unsigned*)(lds + (bufoff) + ldsw + _i * 8192), 16, 0, 0); } while (0)
; #define PG8_LDA(dst, b, h) do { _Pragma("unroll") for (int m = 0; m < 4; ++m) _Pragma("unroll") for (int k = 0; k < 2; ++k) dst[m][k] = *(const PG8_LAS bf16x8*)(lds + PG8_SA(b, h) + aoff + m * 2048 + k * 1024); } while (0)
; #define PG8_LDB(dst, b, h) do { _Pragma("unroll") for (int n = 0; n < 2; ++n) _Pragma("unroll") for (int k = 0; k < 2; ++k) dst[n][k] = *(const PG8_LAS bf16x8*)(lds + PG8_SB(b, h) + boff + n * 2048 + k * 1024); } while (0)
; #define PG8_MMA(ai, bj, At, Bt) do { __builtin_amdgcn_s_setprio(1); _Pragma("unroll") for (int m = 0; m < 4; ++m) _Pragma("unroll") for (int n = 0; n < 2; ++n) _Pragma("unroll") for (int k = 0; k < 2; ++k) \
;         acc[ai][bj][m][n] = __builtin_amdgcn_mfma_f32_16x16x32_bf16(Bt[n][k], At[m][k], acc[ai][bj][m][n], 0, 0, 0); __builtin_amdgcn_s_setprio(0); } while (0)
; #define PG8_WAIT_V(n) asm volatile("s_waitcnt vmcnt(" #n ")" ::: "memory")
; #define PG8_WAIT_L(n) asm volatile("s_waitcnt lgkmcnt(" #n ")" ::: "memory")
; #define PG8_BAR __builtin_amdgcn_s_barrier()
; #define PG8_SCHED __builtin_amdgcn_sched_barrier(0)
; template <class Epi, class Sched, bool ALIGN_EPI = false, bool SP2 = false>
; __device__ __forceinline__ void gemm_phase(PG8_LAS unsigned char* lds, const Gemm g, const Sched& S, const Epi& E) {
;     ...
;             PG8_WAIT_V(8); PG8_WAIT_L(0); PG8_BAR; PG8_MMA(1, 0, At, B0); PG8_MMA(1, 1, At, B1); PG8_BAR; PG8_SCHED;
;             PG8_LDB(B0, 1, 0); PG8_LDB(B1, 1, 1); PG8_SCHED; PG8_LDA(At, 1, 0); PG8_STAGE(PG8_SA(0, 1), a2 + hstep, voffA);
;             PG8_WAIT_V(8); PG8_WAIT_L(0); PG8_BAR; PG8_MMA(0, 0, At, B0); PG8_MMA(0, 1, At, B1); PG8_BAR; PG8_SCHED;
	s_setprio 1
	s_waitcnt lgkmcnt(0)
	v_mfma_f32_16x16x32_bf16 v[62:65], v[110:113], v[162:165], v[62:65]
	v_mfma_f32_16x16x32_bf16 v[62:65], v[118:121], v[166:169], v[62:65]
	v_mfma_f32_16x16x32_bf16 v[46:49], v[110:113], v[170:173], v[46:49]
	v_mfma_f32_16x16x32_bf16 v[46:49], v[118:121], v[174:177], v[46:49]
	v_mfma_f32_16x16x32_bf16 v[30:33], v[110:113], v[178:181], v[30:33]
	v_mfma_f32_16x16x32_bf16 v[30:33], v[118:121], v[182:185], v[30:33]
	v_mfma_f32_16x16x32_bf16 v[14:17], v[110:113], v[186:189], v[14:17]
	v_mfma_f32_16x16x32_bf16 v[14:17], v[118:121], v[190:193], v[14:17]
	v_mfma_f32_16x16x32_bf16 v[54:57], v[146:149], v[162:165], v[54:57]
	v_mfma_f32_16x16x32_bf16 v[54:57], v[150:153], v[166:169], v[54:57]
	v_mfma_f32_16x16x32_bf16 v[38:41], v[146:149], v[170:173], v[38:41]
	v_mfma_f32_16x16x32_bf16 v[38:41], v[150:153], v[174:177], v[38:41]
	v_mfma_f32_16x16x32_bf16 v[22:25], v[146:149], v[178:181], v[22:25]
	v_mfma_f32_16x16x32_bf16 v[22:25], v[150:153], v[182:185], v[22:25]
	v_mfma_f32_16x16x32_bf16 v[6:9], v[146:149], v[186:189], v[6:9]
	v_mfma_f32_16x16x32_bf16 v[6:9], v[150:153], v[190:193], v[6:9]
	v_mfma_f32_16x16x32_bf16 v[58:61], v[138:141], v[162:165], v[58:61]
	v_mfma_f32_16x16x32_bf16 v[58:61], v[142:145], v[166:169], v[58:61]
	v_mfma_f32_16x16x32_bf16 v[42:45], v[138:141], v[170:173], v[42:45]
	v_mfma_f32_16x16x32_bf16 v[42:45], v[142:145], v[174:177], v[42:45]
	v_mfma_f32_16x16x32_bf16 v[26:29], v[138:141], v[178:181], v[26:29]
	v_mfma_f32_16x16x32_bf16 v[26:29], v[142:145], v[182:185], v[26:29]
	v_mfma_f32_16x16x32_bf16 v[10:13], v[138:141], v[186:189], v[10:13]
	v_mfma_f32_16x16x32_bf16 v[10:13], v[142:145], v[190:193], v[10:13]
	v_mfma_f32_16x16x32_bf16 v[50:53], v[154:157], v[162:165], v[50:53]
	v_mfma_f32_16x16x32_bf16 v[50:53], v[158:161], v[166:169], v[50:53]
	v_mfma_f32_16x16x32_bf16 v[34:37], v[154:157], v[170:173], v[34:37]
	v_mfma_f32_16x16x32_bf16 v[34:37], v[158:161], v[174:177], v[34:37]
	v_mfma_f32_16x16x32_bf16 v[18:21], v[154:157], v[178:181], v[18:21]
	v_mfma_f32_16x16x32_bf16 v[18:21], v[158:161], v[182:185], v[18:21]
	v_mfma_f32_16x16x32_bf16 v[2:5], v[154:157], v[186:189], v[2:5]
	v_mfma_f32_16x16x32_bf16 v[2:5], v[158:161], v[190:193], v[2:5]
	s_setprio 0
	s_barrier
	s_add_i32 s18, 0, 0x18000
	s_add_i32 vcc_hi, 0, 0x1c000
	v_add_u32_e32 v142, s18, v245
	v_add_u32_e32 v158, vcc_hi, v245
	ds_read_b128 v[110:113], v142
	ds_read_b128 v[118:121], v142 offset:1024
	ds_read_b128 v[138:141], v142 offset:2048
	ds_read_b128 v[142:145], v142 offset:3072
	ds_read_b128 v[146:149], v158
	ds_read_b128 v[150:153], v158 offset:1024
	ds_read_b128 v[154:157], v158 offset:2048
	ds_read_b128 v[158:161], v158 offset:3072
	s_add_u32 s38, s46, s58
	s_addc_u32 s39, s47, 0
	s_mov_b32 m0, s94
	v_lshl_add_u64 v[222:223], s[38:39], 0, v[194:195]
	ds_read_b128 v[162:165], v247 offset:32768
	ds_read_b128 v[166:169], v247 offset:33792
	ds_read_b128 v[170:173], v247 offset:34816
	ds_read_b128 v[174:177], v247 offset:35840
	ds_read_b128 v[178:181], v247 offset:36864
	ds_read_b128 v[182:185], v247 offset:37888
	ds_read_b128 v[186:189], v247 offset:38912
	ds_read_b128 v[190:193], v247 offset:39936
	global_load_lds_dwordx4 v[222:223], off
	v_lshl_add_u64 v[222:223], s[38:39], 0, v[202:203]
	s_mov_b32 m0, s95
	s_nop 0
	global_load_lds_dwordx4 v[222:223], off
	s_waitcnt vmcnt(8)
	s_waitcnt lgkmcnt(0)
	s_barrier
	s_setprio 1
	s_waitcnt lgkmcnt(0)
	v_mfma_f32_16x16x32_bf16 v[130:133], v[110:113], v[162:165], v[130:133]
	v_mfma_f32_16x16x32_bf16 v[130:133], v[118:121], v[166:169], v[130:133]
	v_mfma_f32_16x16x32_bf16 v[114:117], v[110:113], v[170:173], v[114:117]
	v_mfma_f32_16x16x32_bf16 v[114:117], v[118:121], v[174:177], v[114:117]
	v_mfma_f32_16x16x32_bf16 v[94:97], v[110:113], v[178:181], v[94:97]
	v_mfma_f32_16x16x32_bf16 v[94:97], v[118:121], v[182:185], v[94:97]
	v_mfma_f32_16x16x32_bf16 v[78:81], v[110:113], v[186:189], v[78:81]
	v_mfma_f32_16x16x32_bf16 v[78:81], v[118:121], v[190:193], v[78:81]
	v_mfma_f32_16x16x32_bf16 v[126:129], v[146:149], v[162:165], v[126:129]
	v_mfma_f32_16x16x32_bf16 v[126:129], v[150:153], v[166:169], v[126:129]
	v_mfma_f32_16x16x32_bf16 v[102:105], v[146:149], v[170:173], v[102:105]
	v_mfma_f32_16x16x32_bf16 v[102:105], v[150:153], v[174:177], v[102:105]
	v_mfma_f32_16x16x32_bf16 v[86:89], v[146:149], v[178:181], v[86:89]
	v_mfma_f32_16x16x32_bf16 v[86:89], v[150:153], v[182:185], v[86:89]
	v_mfma_f32_16x16x32_bf16 v[70:73], v[146:149], v[186:189], v[70:73]
	v_mfma_f32_16x16x32_bf16 v[70:73], v[150:153], v[190:193], v[70:73]
	v_mfma_f32_16x16x32_bf16 v[134:137], v[138:141], v[162:165], v[134:137]
	v_mfma_f32_16x16x32_bf16 v[134:137], v[142:145], v[166:169], v[134:137]
	v_mfma_f32_16x16x32_bf16 v[106:109], v[138:141], v[170:173], v[106:109]
	v_mfma_f32_16x16x32_bf16 v[106:109], v[142:145], v[174:177], v[106:109]
	v_mfma_f32_16x16x32_bf16 v[90:93], v[138:141], v[178:181], v[90:93]
	v_mfma_f32_16x16x32_bf16 v[90:93], v[142:145], v[182:185], v[90:93]
	v_mfma_f32_16x16x32_bf16 v[74:77], v[138:141], v[186:189], v[74:77]
	v_mfma_f32_16x16x32_bf16 v[74:77], v[142:145], v[190:193], v[74:77]
	v_mfma_f32_16x16x32_bf16 v[122:125], v[154:157], v[162:165], v[122:125]
	v_mfma_f32_16x16x32_bf16 v[122:125], v[158:161], v[166:169], v[122:125]
	v_mfma_f32_16x16x32_bf16 v[98:101], v[154:157], v[170:173], v[98:101]
	v_mfma_f32_16x16x32_bf16 v[98:101], v[158:161], v[174:177], v[98:101]
	v_mfma_f32_16x16x32_bf16 v[82:85], v[154:157], v[178:181], v[82:85]
	v_mfma_f32_16x16x32_bf16 v[82:85], v[158:161], v[182:185], v[82:85]
	v_mfma_f32_16x16x32_bf16 v[66:69], v[154:157], v[186:189], v[66:69]
	v_mfma_f32_16x16x32_bf16 v[66:69], v[158:161], v[190:193], v[66:69]
	s_setprio 0
	s_barrier
; #define PG8_STAGE(bufoff, gbase, voff) do { _Pragma("unroll") for (int _i = 0; _i < 2; ++_i) \
;         __builtin_amdgcn_global_load_lds((const unsigned*)((const char*)(gbase) + (voff)[_i]), (PG8_LAS unsigned*)(lds + (bufoff) + ldsw + _i * 8192), 16, 0, 0); } while (0)
; #define PG8_LDA(dst, b, h) do { _Pragma("unroll") for (int m = 0; m < 4; ++m) _Pragma("unroll") for (int k = 0; k < 2; ++k) dst[m][k] = *(const PG8_LAS bf16x8*)(lds + PG8_SA(b, h) + aoff + m * 2048 + k * 1024); } while (0)
; #define PG8_MMA(ai, bj, At, Bt) do { __builtin_amdgcn_s_setprio(1); _Pragma("unroll") for (int m = 0; m < 4; ++m) _Pragma("unroll") for (int n = 0; n < 2; ++n) _Pragma("unroll") for (int k = 0; k < 2; ++k) \
;         acc[ai][bj][m][n] = __builtin_amdgcn_mfma_f32_16x16x32_bf16(Bt[n][k], At[m][k], acc[ai][bj][m][n], 0, 0, 0); __builtin_amdgcn_s_setprio(0); } while (0)
; #define PG8_WAIT_V(n) asm volatile("s_waitcnt vmcnt(" #n ")" ::: "memory")
; #define PG8_WAIT_L(n) asm volatile("s_waitcnt lgkmcnt(" #n ")" ::: "memory")
; #define PG8_BAR __builtin_amdgcn_s_barrier()
; #define PG8_SCHED __builtin_amdgcn_sched_barrier(0)
; template <class Epi, class Sched, bool ALIGN_EPI = false, bool SP2 = false>
; __device__ __forceinline__ void gemm_phase(PG8_LAS unsigned char* lds, const Gemm g, const Sched& S, const Epi& E) {
;     ...
;             PG8_LDA(At, 1, 1); PG8_STAGE(PG8_SB(1, 0), b3, voffB); PG8_STAGE(PG8_SB(1, 1), b3 + hstep, voffB); PG8_STAGE(PG8_SA(1, 0), a3, voffA);
;             PG8_WAIT_V(8); PG8_WAIT_L(0); PG8_BAR; PG8_MMA(1, 0, At, B0); PG8_MMA(1, 1, At, B1); PG8_BAR; PG8_SCHED;
	s_add_i32 s18, s18, s6
	v_lshl_add_u64 v[210:211], v[210:211], 0, s[30:31]
	s_mov_b32 m0, s18
	ds_read_b128 v[162:165], v247 offset:49152
	ds_read_b128 v[166:169], v247 offset:50176
	ds_read_b128 v[170:173], v247 offset:51200
	ds_read_b128 v[174:177], v247 offset:52224
	ds_read_b128 v[178:181], v247 offset:53248
	ds_read_b128 v[182:185], v247 offset:54272
	ds_read_b128 v[186:189], v247 offset:55296
	ds_read_b128 v[190:193], v247 offset:56320
	global_load_lds_dwordx4 v[210:211], off
	v_lshl_add_u64 v[210:211], v[212:213], 0, s[30:31]
	s_add_i32 m0, s18, 0x2000
	s_add_i32 s18, vcc_hi, s6
	global_load_lds_dwordx4 v[210:211], off
	v_lshl_add_u64 v[210:211], v[214:215], 0, s[30:31]
	s_mov_b32 m0, s18
	s_nop 0
	global_load_lds_dwordx4 v[210:211], off
	v_lshl_add_u64 v[210:211], v[216:217], 0, s[30:31]
	s_add_i32 m0, s18, 0x2000
	s_nop 0
	global_load_lds_dwordx4 v[210:211], off
	v_lshl_add_u64 v[210:211], v[218:219], 0, s[30:31]
	s_mov_b32 m0, s97
	s_nop 0
	global_load_lds_dwordx4 v[210:211], off
	v_lshl_add_u64 v[210:211], v[220:221], 0, s[30:31]
	s_mov_b32 m0, s98
	s_nop 0
	global_load_lds_dwordx4 v[210:211], off
	s_waitcnt vmcnt(8)
	s_waitcnt lgkmcnt(0)
	s_barrier
	s_setprio 1
	s_waitcnt lgkmcnt(0)
	v_mfma_f32_16x16x32_bf16 v[62:65], v[110:113], v[162:165], v[62:65]
	v_mfma_f32_16x16x32_bf16 v[62:65], v[118:121], v[166:169], v[62:65]
	v_mfma_f32_16x16x32_bf16 v[46:49], v[110:113], v[170:173], v[46:49]
	v_mfma_f32_16x16x32_bf16 v[46:49], v[118:121], v[174:177], v[46:49]
	v_mfma_f32_16x16x32_bf16 v[30:33], v[110:113], v[178:181], v[30:33]
	v_mfma_f32_16x16x32_bf16 v[30:33], v[118:121], v[182:185], v[30:33]
	v_mfma_f32_16x16x32_bf16 v[14:17], v[110:113], v[186:189], v[14:17]
	v_mfma_f32_16x16x32_bf16 v[14:17], v[118:121], v[190:193], v[14:17]
	v_mfma_f32_16x16x32_bf16 v[54:57], v[146:149], v[162:165], v[54:57]
	v_mfma_f32_16x16x32_bf16 v[54:57], v[150:153], v[166:169], v[54:57]
	v_mfma_f32_16x16x32_bf16 v[38:41], v[146:149], v[170:173], v[38:41]
	v_mfma_f32_16x16x32_bf16 v[38:41], v[150:153], v[174:177], v[38:41]
	v_mfma_f32_16x16x32_bf16 v[22:25], v[146:149], v[178:181], v[22:25]
	v_mfma_f32_16x16x32_bf16 v[22:25], v[150:153], v[182:185], v[22:25]
	v_mfma_f32_16x16x32_bf16 v[6:9], v[146:149], v[186:189], v[6:9]
	v_mfma_f32_16x16x32_bf16 v[6:9], v[150:153], v[190:193], v[6:9]
	v_mfma_f32_16x16x32_bf16 v[58:61], v[138:141], v[162:165], v[58:61]
	v_mfma_f32_16x16x32_bf16 v[58:61], v[142:145], v[166:169], v[58:61]
	v_mfma_f32_16x16x32_bf16 v[42:45], v[138:141], v[170:173], v[42:45]
	v_mfma_f32_16x16x32_bf16 v[42:45], v[142:145], v[174:177], v[42:45]
	v_mfma_f32_16x16x32_bf16 v[26:29], v[138:141], v[178:181], v[26:29]
	v_mfma_f32_16x16x32_bf16 v[26:29], v[142:145], v[182:185], v[26:29]
	v_mfma_f32_16x16x32_bf16 v[10:13], v[138:141], v[186:189], v[10:13]
	v_mfma_f32_16x16x32_bf16 v[10:13], v[142:145], v[190:193], v[10:13]
	v_mfma_f32_16x16x32_bf16 v[50:53], v[154:157], v[162:165], v[50:53]
	v_mfma_f32_16x16x32_bf16 v[50:53], v[158:161], v[166:169], v[50:53]
	v_mfma_f32_16x16x32_bf16 v[34:37], v[154:157], v[170:173], v[34:37]
	v_mfma_f32_16x16x32_bf16 v[34:37], v[158:161], v[174:177], v[34:37]
	v_mfma_f32_16x16x32_bf16 v[18:21], v[154:157], v[178:181], v[18:21]
	v_mfma_f32_16x16x32_bf16 v[18:21], v[158:161], v[182:185], v[18:21]
	v_mfma_f32_16x16x32_bf16 v[2:5], v[154:157], v[186:189], v[2:5]
	v_mfma_f32_16x16x32_bf16 v[2:5], v[158:161], v[190:193], v[2:5]
	s_setprio 0
	s_barrier
	s_add_u32 s48, s48, 0x100
	s_addc_u32 s49, s49, 0
	s_add_u32 s50, s50, 0x100
	s_addc_u32 s51, s51, 0
	s_cmp_ge_u32 vcc_lo, s96
	s_mov_b32 s46, vcc_lo
	s_cbranch_scc0 .LBB0_274
	s_and_b64 vcc, exec, s[72:73]
	s_cbranch_vccz .LBB0_277
	s_barrier

; #define PG8_STAGE(bufoff, gbase, voff) do { _Pragma("unroll") for (int _i = 0; _i < 2; ++_i) \
;         __builtin_amdgcn_global_load_lds((const unsigned*)((const char*)(gbase) + (voff)[_i]), (PG8_LAS unsigned*)(lds + (bufoff) + ldsw + _i * 8192), 16, 0, 0); } while (0)
; #define PG8_LDA(dst, b, h) do { _Pragma("unroll") for (int m = 0; m < 4; ++m) _Pragma("unroll") for (int k = 0; k < 2; ++k) dst[m][k] = *(const PG8_LAS bf16x8*)(lds + PG8_SA(b, h) + aoff + m * 2048 + k * 1024); } while (0)
; #define PG8_LDB(dst, b, h) do { _Pragma("unroll") for (int n = 0; n < 2; ++n) _Pragma("unroll") for (int k = 0; k < 2; ++k) dst[n][k] = *(const PG8_LAS bf16x8*)(lds + PG8_SB(b, h) + boff + n * 2048 + k * 1024); } while (0)
; #define PG8_MMA(ai, bj, At, Bt) do { __builtin_amdgcn_s_setprio(1); _Pragma("unroll") for (int m = 0; m < 4; ++m) _Pragma("unroll") for (int n = 0; n < 2; ++n) _Pragma("unroll") for (int k = 0; k < 2; ++k) \
;         acc[ai][bj][m][n] = __builtin_amdgcn_mfma_f32_16x16x32_bf16(Bt[n][k], At[m][k], acc[ai][bj][m][n], 0, 0, 0); __builtin_amdgcn_s_setprio(0); } while (0)
; #define PG8_WAIT_V(n) asm volatile("s_waitcnt vmcnt(" #n ")" ::: "memory")
; #define PG8_WAIT_L(n) asm volatile("s_waitcnt lgkmcnt(" #n ")" ::: "memory")
; template <class Epi, class Sched, bool ALIGN_EPI = false, bool SP2 = false>
; __device__ __forceinline__ void gemm_phase(PG8_LAS unsigned char* lds, const Gemm g, const Sched& S, const Epi& E) {
;     ...
;             const bool last = (t == nt - 2);
;             const char* a1 = cA + (size_t)(t + 1) * kstep;
;             const char* a2 = last ? nA : cA + (size_t)(t + 2) * kstep; const char* b2 = last ? nB : cB + (size_t)(t + 2) * kstep;
;             const char* a3 = a2 + kstep; const char* b3 = b2 + kstep;
;             if (last && has_next) S.a_ready(nxt);
;             if constexpr (SP2) {
;             PG8_LDB(B0, 0, 0); PG8_LDB(B1, 0, 1); PG8_SCHED; PG8_LDA(At, 0, 0); PG8_STAGE(PG8_SA(1, 1), a1 + hstep, voffA);
;             PG8_WAIT_V(8); PG8_WAIT_L(0); PG8_BAR; PG8_MMA(0, 0, At, B0); PG8_MMA(0, 1, At, B1); PG8_BAR; PG8_SCHED;
;             PG8_LDA(At, 0, 1); PG8_STAGE(PG8_SB(0, 0), b2, voffB); PG8_STAGE(PG8_SB(0, 1), b2 + hstep, voffB); PG8_STAGE(PG8_SA(0, 0), a2, voffA);
;             PG8_WAIT_V(8); PG8_WAIT_L(0); PG8_BAR; PG8_MMA(1, 0, At, B0); PG8_MMA(1, 1, At, B1); PG8_BAR; PG8_SCHED;
.LBB0_408:
	s_add_u32 s38, s48, 0xfffc0080
	s_addc_u32 s39, s49, -1
	s_add_i32 s85, 0, 0x10000
	s_cmp_eq_u32 s84, 12
	s_cselect_b32 s73, s21, s39
	s_cselect_b32 s72, s27, s38
	v_add_u32_e32 v0, s85, v167
	s_cselect_b32 s47, s29, s69
	s_cselect_b32 s46, s33, s53
	s_add_i32 s38, 0, 0x14000
	ds_read_b128 v[142:145], v0
	ds_read_b128 v[146:149], v0 offset:1024
	ds_read_b128 v[150:153], v0 offset:2048
	ds_read_b128 v[154:157], v0 offset:3072
	v_add_u32_e32 v0, s38, v167
	ds_read_b128 v[158:161], v0
	ds_read_b128 v[162:165], v0 offset:1024
	ds_read_b128 v[172:175], v0 offset:2048
	ds_read_b128 v[176:179], v0 offset:3072
	v_lshl_add_u64 v[218:219], s[48:49], 0, v[138:139]
	s_add_i32 m0, s76, 0xc000
	ds_read_b128 v[180:183], v170
	ds_read_b128 v[184:187], v170 offset:1024
	ds_read_b128 v[188:191], v170 offset:2048
	ds_read_b128 v[192:195], v170 offset:3072
	ds_read_b128 v[202:205], v170 offset:4096
	ds_read_b128 v[206:209], v170 offset:5120
	ds_read_b128 v[210:213], v170 offset:6144
	ds_read_b128 v[214:217], v170 offset:7168
	global_load_lds_dwordx4 v[218:219], off
	v_lshl_add_u64 v[218:219], s[48:49], 0, v[140:141]
	s_add_i32 m0, s76, 0xe000
	s_nop 0
	global_load_lds_dwordx4 v[218:219], off
	s_waitcnt vmcnt(8)
	s_waitcnt lgkmcnt(0)
	s_barrier
	s_setprio 1
	s_waitcnt lgkmcnt(0)
	v_mfma_f32_16x16x32_bf16 v[122:125], v[142:145], v[180:183], v[122:125]
	v_mfma_f32_16x16x32_bf16 v[122:125], v[146:149], v[184:187], v[122:125]
	v_mfma_f32_16x16x32_bf16 v[106:109], v[142:145], v[188:191], v[106:109]
	v_mfma_f32_16x16x32_bf16 v[106:109], v[146:149], v[192:195], v[106:109]
	v_mfma_f32_16x16x32_bf16 v[90:93], v[142:145], v[202:205], v[90:93]
	v_mfma_f32_16x16x32_bf16 v[90:93], v[146:149], v[206:209], v[90:93]
	v_mfma_f32_16x16x32_bf16 v[74:77], v[142:145], v[210:213], v[74:77]
	v_mfma_f32_16x16x32_bf16 v[74:77], v[146:149], v[214:217], v[74:77]
	v_mfma_f32_16x16x32_bf16 v[114:117], v[158:161], v[180:183], v[114:117]
	v_mfma_f32_16x16x32_bf16 v[114:117], v[162:165], v[184:187], v[114:117]
	v_mfma_f32_16x16x32_bf16 v[98:101], v[158:161], v[188:191], v[98:101]
	v_mfma_f32_16x16x32_bf16 v[98:101], v[162:165], v[192:195], v[98:101]
	v_mfma_f32_16x16x32_bf16 v[82:85], v[158:161], v[202:205], v[82:85]
	v_mfma_f32_16x16x32_bf16 v[82:85], v[162:165], v[206:209], v[82:85]
	v_mfma_f32_16x16x32_bf16 v[66:69], v[158:161], v[210:213], v[66:69]
	v_mfma_f32_16x16x32_bf16 v[66:69], v[162:165], v[214:217], v[66:69]
	v_mfma_f32_16x16x32_bf16 v[126:129], v[150:153], v[180:183], v[126:129]
	v_mfma_f32_16x16x32_bf16 v[126:129], v[154:157], v[184:187], v[126:129]
	v_mfma_f32_16x16x32_bf16 v[110:113], v[150:153], v[188:191], v[110:113]
	v_mfma_f32_16x16x32_bf16 v[110:113], v[154:157], v[192:195], v[110:113]
	v_mfma_f32_16x16x32_bf16 v[94:97], v[150:153], v[202:205], v[94:97]
	v_mfma_f32_16x16x32_bf16 v[94:97], v[154:157], v[206:209], v[94:97]
	v_mfma_f32_16x16x32_bf16 v[78:81], v[150:153], v[210:213], v[78:81]
	v_mfma_f32_16x16x32_bf16 v[78:81], v[154:157], v[214:217], v[78:81]
	v_mfma_f32_16x16x32_bf16 v[118:121], v[172:175], v[180:183], v[118:121]
	v_mfma_f32_16x16x32_bf16 v[118:121], v[176:179], v[184:187], v[118:121]
	v_mfma_f32_16x16x32_bf16 v[102:105], v[172:175], v[188:191], v[102:105]
	v_mfma_f32_16x16x32_bf16 v[102:105], v[176:179], v[192:195], v[102:105]
	v_mfma_f32_16x16x32_bf16 v[86:89], v[172:175], v[202:205], v[86:89]
	v_mfma_f32_16x16x32_bf16 v[86:89], v[176:179], v[206:209], v[86:89]
	v_mfma_f32_16x16x32_bf16 v[70:73], v[172:175], v[210:213], v[70:73]
	v_mfma_f32_16x16x32_bf16 v[70:73], v[176:179], v[214:217], v[70:73]
	s_setprio 0
	s_barrier
	s_add_i32 s39, s85, s75
	v_lshl_add_u64 v[218:219], s[46:47], 0, v[134:135]
	s_mov_b32 m0, s39
	ds_read_b128 v[180:183], v170 offset:16384
	ds_read_b128 v[184:187], v170 offset:17408
	ds_read_b128 v[188:191], v170 offset:18432
	ds_read_b128 v[192:195], v170 offset:19456
	ds_read_b128 v[202:205], v170 offset:20480
	ds_read_b128 v[206:209], v170 offset:21504
	ds_read_b128 v[210:213], v170 offset:22528
	ds_read_b128 v[214:217], v170 offset:23552
	global_load_lds_dwordx4 v[218:219], off
	s_add_i32 m0, s39, 0x2000
	s_add_u32 s92, s46, 0x40000
	v_lshl_add_u64 v[220:221], s[46:47], 0, v[130:131]
	s_addc_u32 s93, s47, 0
	s_add_i32 s38, s38, s75
	global_load_lds_dwordx4 v[220:221], off
	v_lshl_add_u64 v[222:223], s[92:93], 0, v[134:135]
	s_mov_b32 m0, s38
	v_lshl_add_u64 v[224:225], s[72:73], 0, v[132:133]
	global_load_lds_dwordx4 v[222:223], off
	v_lshl_add_u64 v[222:223], s[92:93], 0, v[130:131]
	s_add_i32 m0, s38, 0x2000
	s_nop 0
	global_load_lds_dwordx4 v[222:223], off
	v_lshl_add_u64 v[222:223], s[72:73], 0, v[136:137]
	s_mov_b32 m0, s76
	s_nop 0
	global_load_lds_dwordx4 v[222:223], off
	s_mov_b32 m0, s77
	s_nop 0
	global_load_lds_dwordx4 v[224:225], off
	s_waitcnt vmcnt(8)
	s_waitcnt lgkmcnt(0)
	s_barrier
; #define PG8_STAGE(bufoff, gbase, voff) do { _Pragma("unroll") for (int _i = 0; _i < 2; ++_i) \
;         __builtin_amdgcn_global_load_lds((const unsigned*)((const char*)(gbase) + (voff)[_i]), (PG8_LAS unsigned*)(lds + (bufoff) + ldsw + _i * 8192), 16, 0, 0); } while (0)
; #define PG8_LDA(dst, b, h) do { _Pragma("unroll") for (int m = 0; m < 4; ++m) _Pragma("unroll") for (int k = 0; k < 2; ++k) dst[m][k] = *(const PG8_LAS bf16x8*)(lds + PG8_SA(b, h) + aoff + m * 2048 + k * 1024); } while (0)
; #define PG8_LDB(dst, b, h) do { _Pragma("unroll") for (int n = 0; n < 2; ++n) _Pragma("unroll") for (int k = 0; k < 2; ++k) dst[n][k] = *(const PG8_LAS bf16x8*)(lds + PG8_SB(b, h) + boff + n * 2048 + k * 1024); } while (0)
; #define PG8_MMA(ai, bj, At, Bt) do { __builtin_amdgcn_s_setprio(1); _Pragma("unroll") for (int m = 0; m < 4; ++m) _Pragma("unroll") for (int n = 0; n < 2; ++n) _Pragma("unroll") for (int k = 0; k < 2; ++k) \
;         acc[ai][bj][m][n] = __builtin_amdgcn_mfma_f32_16x16x32_bf16(Bt[n][k], At[m][k], acc[ai][bj][m][n], 0, 0, 0); __builtin_amdgcn_s_setprio(0); } while (0)
; #define PG8_WAIT_V(n) asm volatile("s_waitcnt vmcnt(" #n ")" ::: "memory")
; #define PG8_WAIT_L(n) asm volatile("s_waitcnt lgkmcnt(" #n ")" ::: "memory")
; #define PG8_BAR __builtin_amdgcn_s_barrier()
; #define PG8_SCHED __builtin_amdgcn_sched_barrier(0)
; template <class Epi, class Sched, bool ALIGN_EPI = false, bool SP2 = false>
; __device__ __forceinline__ void gemm_phase(PG8_LAS unsigned char* lds, const Gemm g, const Sched& S, const Epi& E) {
;     ...
;             PG8_WAIT_V(8); PG8_WAIT_L(0); PG8_BAR; PG8_MMA(1, 0, At, B0); PG8_MMA(1, 1, At, B1); PG8_BAR; PG8_SCHED;
;             PG8_LDB(B0, 1, 0); PG8_LDB(B1, 1, 1); PG8_SCHED; PG8_LDA(At, 1, 0); PG8_STAGE(PG8_SA(0, 1), a2 + hstep, voffA);
;             PG8_WAIT_V(8); PG8_WAIT_L(0); PG8_BAR; PG8_MMA(0, 0, At, B0); PG8_MMA(0, 1, At, B1); PG8_BAR; PG8_SCHED;
	s_setprio 1
	s_waitcnt lgkmcnt(0)
	v_mfma_f32_16x16x32_bf16 v[58:61], v[142:145], v[180:183], v[58:61]
	v_mfma_f32_16x16x32_bf16 v[58:61], v[146:149], v[184:187], v[58:61]
	v_mfma_f32_16x16x32_bf16 v[42:45], v[142:145], v[188:191], v[42:45]
	v_mfma_f32_16x16x32_bf16 v[42:45], v[146:149], v[192:195], v[42:45]
	v_mfma_f32_16x16x32_bf16 v[26:29], v[142:145], v[202:205], v[26:29]
	v_mfma_f32_16x16x32_bf16 v[26:29], v[146:149], v[206:209], v[26:29]
	v_mfma_f32_16x16x32_bf16 v[10:13], v[142:145], v[210:213], v[10:13]
	v_mfma_f32_16x16x32_bf16 v[10:13], v[146:149], v[214:217], v[10:13]
	v_mfma_f32_16x16x32_bf16 v[50:53], v[158:161], v[180:183], v[50:53]
	v_mfma_f32_16x16x32_bf16 v[50:53], v[162:165], v[184:187], v[50:53]
	v_mfma_f32_16x16x32_bf16 v[34:37], v[158:161], v[188:191], v[34:37]
	v_mfma_f32_16x16x32_bf16 v[34:37], v[162:165], v[192:195], v[34:37]
	v_mfma_f32_16x16x32_bf16 v[18:21], v[158:161], v[202:205], v[18:21]
	v_mfma_f32_16x16x32_bf16 v[18:21], v[162:165], v[206:209], v[18:21]
	v_mfma_f32_16x16x32_bf16 v[2:5], v[158:161], v[210:213], v[2:5]
	v_mfma_f32_16x16x32_bf16 v[2:5], v[162:165], v[214:217], v[2:5]
	v_mfma_f32_16x16x32_bf16 v[62:65], v[150:153], v[180:183], v[62:65]
	v_mfma_f32_16x16x32_bf16 v[62:65], v[154:157], v[184:187], v[62:65]
	v_mfma_f32_16x16x32_bf16 v[46:49], v[150:153], v[188:191], v[46:49]
	v_mfma_f32_16x16x32_bf16 v[46:49], v[154:157], v[192:195], v[46:49]
	v_mfma_f32_16x16x32_bf16 v[30:33], v[150:153], v[202:205], v[30:33]
	v_mfma_f32_16x16x32_bf16 v[30:33], v[154:157], v[206:209], v[30:33]
	v_mfma_f32_16x16x32_bf16 v[14:17], v[150:153], v[210:213], v[14:17]
	v_mfma_f32_16x16x32_bf16 v[14:17], v[154:157], v[214:217], v[14:17]
	v_mfma_f32_16x16x32_bf16 v[54:57], v[172:175], v[180:183], v[54:57]
	v_mfma_f32_16x16x32_bf16 v[54:57], v[176:179], v[184:187], v[54:57]
	v_mfma_f32_16x16x32_bf16 v[38:41], v[172:175], v[188:191], v[38:41]
	v_mfma_f32_16x16x32_bf16 v[38:41], v[176:179], v[192:195], v[38:41]
	v_mfma_f32_16x16x32_bf16 v[22:25], v[172:175], v[202:205], v[22:25]
	v_mfma_f32_16x16x32_bf16 v[22:25], v[176:179], v[206:209], v[22:25]
	v_mfma_f32_16x16x32_bf16 v[6:9], v[172:175], v[210:213], v[6:9]
	v_mfma_f32_16x16x32_bf16 v[6:9], v[176:179], v[214:217], v[6:9]
	s_setprio 0
	s_barrier
	s_add_i32 s38, 0, 0x18000
	v_add_u32_e32 v0, s38, v167
	s_add_i32 s39, 0, 0x1c000
	ds_read_b128 v[142:145], v0
	ds_read_b128 v[146:149], v0 offset:1024
	ds_read_b128 v[150:153], v0 offset:2048
	ds_read_b128 v[154:157], v0 offset:3072
	v_add_u32_e32 v0, s39, v167
	ds_read_b128 v[158:161], v0
	ds_read_b128 v[162:165], v0 offset:1024
	ds_read_b128 v[172:175], v0 offset:2048
	ds_read_b128 v[176:179], v0 offset:3072
	s_add_u32 s72, s72, 0x40000
	s_addc_u32 s73, s73, 0
	s_mov_b32 m0, s78
	v_lshl_add_u64 v[226:227], s[72:73], 0, v[136:137]
	ds_read_b128 v[180:183], v170 offset:32768
	ds_read_b128 v[184:187], v170 offset:33792
	ds_read_b128 v[188:191], v170 offset:34816
	ds_read_b128 v[192:195], v170 offset:35840
	ds_read_b128 v[202:205], v170 offset:36864
	ds_read_b128 v[206:209], v170 offset:37888
	ds_read_b128 v[210:213], v170 offset:38912
	ds_read_b128 v[214:217], v170 offset:39936
	global_load_lds_dwordx4 v[226:227], off
	v_lshl_add_u64 v[226:227], s[72:73], 0, v[132:133]
	s_mov_b32 m0, s79
	s_nop 0
	global_load_lds_dwordx4 v[226:227], off
	s_waitcnt vmcnt(8)
	s_waitcnt lgkmcnt(0)
	s_barrier
	s_setprio 1
	s_waitcnt lgkmcnt(0)
	v_mfma_f32_16x16x32_bf16 v[122:125], v[142:145], v[180:183], v[122:125]
	v_mfma_f32_16x16x32_bf16 v[122:125], v[146:149], v[184:187], v[122:125]
	v_mfma_f32_16x16x32_bf16 v[106:109], v[142:145], v[188:191], v[106:109]
	v_mfma_f32_16x16x32_bf16 v[106:109], v[146:149], v[192:195], v[106:109]
	v_mfma_f32_16x16x32_bf16 v[90:93], v[142:145], v[202:205], v[90:93]
	v_mfma_f32_16x16x32_bf16 v[90:93], v[146:149], v[206:209], v[90:93]
	v_mfma_f32_16x16x32_bf16 v[74:77], v[142:145], v[210:213], v[74:77]
	v_mfma_f32_16x16x32_bf16 v[74:77], v[146:149], v[214:217], v[74:77]
	v_mfma_f32_16x16x32_bf16 v[114:117], v[158:161], v[180:183], v[114:117]
	v_mfma_f32_16x16x32_bf16 v[114:117], v[162:165], v[184:187], v[114:117]
	v_mfma_f32_16x16x32_bf16 v[98:101], v[158:161], v[188:191], v[98:101]
	v_mfma_f32_16x16x32_bf16 v[98:101], v[162:165], v[192:195], v[98:101]
	v_mfma_f32_16x16x32_bf16 v[82:85], v[158:161], v[202:205], v[82:85]
	v_mfma_f32_16x16x32_bf16 v[82:85], v[162:165], v[206:209], v[82:85]
	v_mfma_f32_16x16x32_bf16 v[66:69], v[158:161], v[210:213], v[66:69]
	v_mfma_f32_16x16x32_bf16 v[66:69], v[162:165], v[214:217], v[66:69]
	v_mfma_f32_16x16x32_bf16 v[126:129], v[150:153], v[180:183], v[126:129]
	v_mfma_f32_16x16x32_bf16 v[126:129], v[154:157], v[184:187], v[126:129]
	v_mfma_f32_16x16x32_bf16 v[110:113], v[150:153], v[188:191], v[110:113]
	v_mfma_f32_16x16x32_bf16 v[110:113], v[154:157], v[192:195], v[110:113]
	v_mfma_f32_16x16x32_bf16 v[94:97], v[150:153], v[202:205], v[94:97]
	v_mfma_f32_16x16x32_bf16 v[94:97], v[154:157], v[206:209], v[94:97]
	v_mfma_f32_16x16x32_bf16 v[78:81], v[150:153], v[210:213], v[78:81]
	v_mfma_f32_16x16x32_bf16 v[78:81], v[154:157], v[214:217], v[78:81]
	v_mfma_f32_16x16x32_bf16 v[118:121], v[172:175], v[180:183], v[118:121]
	v_mfma_f32_16x16x32_bf16 v[118:121], v[176:179], v[184:187], v[118:121]
	v_mfma_f32_16x16x32_bf16 v[102:105], v[172:175], v[188:191], v[102:105]
	v_mfma_f32_16x16x32_bf16 v[102:105], v[176:179], v[192:195], v[102:105]
	v_mfma_f32_16x16x32_bf16 v[86:89], v[172:175], v[202:205], v[86:89]
	v_mfma_f32_16x16x32_bf16 v[86:89], v[176:179], v[206:209], v[86:89]
	v_mfma_f32_16x16x32_bf16 v[70:73], v[172:175], v[210:213], v[70:73]
	v_mfma_f32_16x16x32_bf16 v[70:73], v[176:179], v[214:217], v[70:73]
	s_setprio 0
	s_barrier
; #define PG8_STAGE(bufoff, gbase, voff) do { _Pragma("unroll") for (int _i = 0; _i < 2; ++_i) \
;         __builtin_amdgcn_global_load_lds((const unsigned*)((const char*)(gbase) + (voff)[_i]), (PG8_LAS unsigned*)(lds + (bufoff) + ldsw + _i * 8192), 16, 0, 0); } while (0)
; #define PG8_LDA(dst, b, h) do { _Pragma("unroll") for (int m = 0; m < 4; ++m) _Pragma("unroll") for (int k = 0; k < 2; ++k) dst[m][k] = *(const PG8_LAS bf16x8*)(lds + PG8_SA(b, h) + aoff + m * 2048 + k * 1024); } while (0)
; #define PG8_MMA(ai, bj, At, Bt) do { __builtin_amdgcn_s_setprio(1); _Pragma("unroll") for (int m = 0; m < 4; ++m) _Pragma("unroll") for (int n = 0; n < 2; ++n) _Pragma("unroll") for (int k = 0; k < 2; ++k) \
;         acc[ai][bj][m][n] = __builtin_amdgcn_mfma_f32_16x16x32_bf16(Bt[n][k], At[m][k], acc[ai][bj][m][n], 0, 0, 0); __builtin_amdgcn_s_setprio(0); } while (0)
; #define PG8_WAIT_V(n) asm volatile("s_waitcnt vmcnt(" #n ")" ::: "memory")
; #define PG8_WAIT_L(n) asm volatile("s_waitcnt lgkmcnt(" #n ")" ::: "memory")
; #define PG8_BAR __builtin_amdgcn_s_barrier()
; #define PG8_SCHED __builtin_amdgcn_sched_barrier(0)
; template <class Epi, class Sched, bool ALIGN_EPI = false, bool SP2 = false>
; __device__ __forceinline__ void gemm_phase(PG8_LAS unsigned char* lds, const Gemm g, const Sched& S, const Epi& E) {
;     ...
;             PG8_LDA(At, 1, 1); PG8_STAGE(PG8_SB(1, 0), b3, voffB); PG8_STAGE(PG8_SB(1, 1), b3 + hstep, voffB); PG8_STAGE(PG8_SA(1, 0), a3, voffA);
;             PG8_WAIT_V(8); PG8_WAIT_L(0); PG8_BAR; PG8_MMA(1, 0, At, B0); PG8_MMA(1, 1, At, B1); PG8_BAR; PG8_SCHED;
	s_add_i32 s38, s38, s75
	v_lshl_add_u64 v[218:219], v[218:219], 0, s[30:31]
	s_mov_b32 m0, s38
	ds_read_b128 v[180:183], v170 offset:49152
	ds_read_b128 v[184:187], v170 offset:50176
	ds_read_b128 v[188:191], v170 offset:51200
	ds_read_b128 v[192:195], v170 offset:52224
	ds_read_b128 v[202:205], v170 offset:53248
	ds_read_b128 v[206:209], v170 offset:54272
	ds_read_b128 v[210:213], v170 offset:55296
	ds_read_b128 v[214:217], v170 offset:56320
	global_load_lds_dwordx4 v[218:219], off
	s_add_i32 m0, s38, 0x2000
	s_add_u32 s46, s46, 0x40080
	v_lshl_add_u64 v[218:219], v[220:221], 0, s[30:31]
	s_addc_u32 s47, s47, 0
	s_add_i32 s38, s39, s75
	global_load_lds_dwordx4 v[218:219], off
	v_lshl_add_u64 v[218:219], s[46:47], 0, v[134:135]
	s_mov_b32 m0, s38
	s_nop 0
	global_load_lds_dwordx4 v[218:219], off
	v_lshl_add_u64 v[218:219], s[46:47], 0, v[130:131]
	s_add_i32 m0, s38, 0x2000
	s_nop 0
	global_load_lds_dwordx4 v[218:219], off
	v_lshl_add_u64 v[218:219], v[222:223], 0, s[30:31]
	s_mov_b32 m0, s80
	s_nop 0
	global_load_lds_dwordx4 v[218:219], off
	v_lshl_add_u64 v[218:219], v[224:225], 0, s[30:31]
	s_mov_b32 m0, s81
	s_nop 0
	global_load_lds_dwordx4 v[218:219], off
	s_waitcnt vmcnt(8)
	s_waitcnt lgkmcnt(0)
	s_barrier
	s_setprio 1
	s_waitcnt lgkmcnt(0)
	v_mfma_f32_16x16x32_bf16 v[58:61], v[142:145], v[180:183], v[58:61]
	v_mfma_f32_16x16x32_bf16 v[58:61], v[146:149], v[184:187], v[58:61]
	v_mfma_f32_16x16x32_bf16 v[42:45], v[142:145], v[188:191], v[42:45]
	v_mfma_f32_16x16x32_bf16 v[42:45], v[146:149], v[192:195], v[42:45]
	v_mfma_f32_16x16x32_bf16 v[26:29], v[142:145], v[202:205], v[26:29]
	v_mfma_f32_16x16x32_bf16 v[26:29], v[146:149], v[206:209], v[26:29]
	v_mfma_f32_16x16x32_bf16 v[10:13], v[142:145], v[210:213], v[10:13]
	v_mfma_f32_16x16x32_bf16 v[10:13], v[146:149], v[214:217], v[10:13]
	v_mfma_f32_16x16x32_bf16 v[50:53], v[158:161], v[180:183], v[50:53]
	v_mfma_f32_16x16x32_bf16 v[50:53], v[162:165], v[184:187], v[50:53]
	v_mfma_f32_16x16x32_bf16 v[34:37], v[158:161], v[188:191], v[34:37]
	v_mfma_f32_16x16x32_bf16 v[34:37], v[162:165], v[192:195], v[34:37]
	v_mfma_f32_16x16x32_bf16 v[18:21], v[158:161], v[202:205], v[18:21]
	v_mfma_f32_16x16x32_bf16 v[18:21], v[162:165], v[206:209], v[18:21]
	v_mfma_f32_16x16x32_bf16 v[2:5], v[158:161], v[210:213], v[2:5]
	v_mfma_f32_16x16x32_bf16 v[2:5], v[162:165], v[214:217], v[2:5]
	v_mfma_f32_16x16x32_bf16 v[62:65], v[150:153], v[180:183], v[62:65]
	v_mfma_f32_16x16x32_bf16 v[62:65], v[154:157], v[184:187], v[62:65]
	v_mfma_f32_16x16x32_bf16 v[46:49], v[150:153], v[188:191], v[46:49]
	v_mfma_f32_16x16x32_bf16 v[46:49], v[154:157], v[192:195], v[46:49]
	v_mfma_f32_16x16x32_bf16 v[30:33], v[150:153], v[202:205], v[30:33]
	v_mfma_f32_16x16x32_bf16 v[30:33], v[154:157], v[206:209], v[30:33]
	v_mfma_f32_16x16x32_bf16 v[14:17], v[150:153], v[210:213], v[14:17]
	v_mfma_f32_16x16x32_bf16 v[14:17], v[154:157], v[214:217], v[14:17]
	v_mfma_f32_16x16x32_bf16 v[54:57], v[172:175], v[180:183], v[54:57]
	v_mfma_f32_16x16x32_bf16 v[54:57], v[176:179], v[184:187], v[54:57]
	v_mfma_f32_16x16x32_bf16 v[38:41], v[172:175], v[188:191], v[38:41]
	v_mfma_f32_16x16x32_bf16 v[38:41], v[176:179], v[192:195], v[38:41]
	v_mfma_f32_16x16x32_bf16 v[22:25], v[172:175], v[202:205], v[22:25]
	v_mfma_f32_16x16x32_bf16 v[22:25], v[176:179], v[206:209], v[22:25]
	v_mfma_f32_16x16x32_bf16 v[6:9], v[172:175], v[210:213], v[6:9]
	v_mfma_f32_16x16x32_bf16 v[6:9], v[176:179], v[214:217], v[6:9]
	s_setprio 0
	s_barrier
	s_add_i32 s84, s84, 2
	s_add_u32 s48, s48, 0x100
	s_addc_u32 s49, s49, 0
	s_add_u32 s53, s53, 0x100
	s_addc_u32 s69, s69, 0
	s_cmp_gt_u32 s84, 13
	s_cbranch_scc0 .LBB0_408
	s_and_b64 vcc, exec, s[64:65]
	s_cbranch_vccz .LBB0_411
	s_barrier
